# static s_setprio 1 for the trailing (younger) half across each GEMM K-loop, per-segment flips removed; on top of v89
# baseline (speedup 1.0000x reference)
; #define PG8_STAGE(bufoff, gbase, voff) do { _Pragma("unroll") for (int _i = 0; _i < 2; ++_i) \
;         __builtin_amdgcn_global_load_lds((const unsigned*)((const char*)(gbase) + (voff)[_i]), (PG8_LAS unsigned*)(lds + (bufoff) + ldsw + _i * 8192), 16, 0, 0); } while (0)
; #define PG8_LDA(dst, b, h) do { _Pragma("unroll") for (int m = 0; m < 4; ++m) _Pragma("unroll") for (int k = 0; k < 2; ++k) dst[m][k] = *(const PG8_LAS bf16x8*)(lds + PG8_SA(b, h) + aoff + m * 2048 + k * 1024); } while (0)
; #define PG8_LDB(dst, b, h) do { _Pragma("unroll") for (int n = 0; n < 2; ++n) _Pragma("unroll") for (int k = 0; k < 2; ++k) dst[n][k] = *(const PG8_LAS bf16x8*)(lds + PG8_SB(b, h) + boff + n * 2048 + k * 1024); } while (0)
; #define PG8_WAIT_V(n) asm volatile("s_waitcnt vmcnt(" #n ")" ::: "memory")
; #define PG8_WAIT_L(n) asm volatile("s_waitcnt lgkmcnt(" #n ")" ::: "memory")
; #define PG8_BAR __builtin_amdgcn_s_barrier()
; template <class Epi, class Sched, bool ALIGN_EPI = false, bool SP2 = false>
; __device__ __forceinline__ void gemm_phase(PG8_LAS unsigned char* lds, const Gemm g, const Sched& S, const Epi& E, const int tid) {
;     ...
;         const bool has_next = S.next(ui + 1, nxt);
;         const char* nA = has_next ? (const char*)g.A + (size_t)nxt.pm * tstep : cA; const char* nB = has_next ? (const char*)g.Bt + (size_t)nxt.pn * tstep : cB;
;         for (int t = 0; t < nt; t += 2) {
;             if constexpr (Epi::MIDK) { if (t == E.midk) E.mid(acc, cur, wr, fr); }
;             const bool last = (t == nt - 2);
;             const char* a1 = cA + (size_t)(t + 1) * kstep;
;             const char* a2 = last ? nA : cA + (size_t)(t + 2) * kstep; const char* b2 = last ? nB : cB + (size_t)(t + 2) * kstep;
;             const char* a3 = a2 + kstep; const char* b3 = b2 + kstep;
;             if (last && has_next) S.a_ready(nxt);
;             if constexpr (SP2) {
;             PG8_LDB(B0, 0, 0); PG8_LDB(B1, 0, 1); PG8_SCHED; PG8_LDA(At, 0, 0); PG8_STAGE(PG8_SA(1, 1), a1 + hstep, voffA);
;             PG8_WAIT_V(8); PG8_WAIT_L(0); PG8_BAR; PG8_MMA(0, 0, At, B0); PG8_MMA(0, 1, At, B1); PG8_BAR; PG8_SCHED;
;             PG8_LDA(At, 0, 1); PG8_STAGE(PG8_SB(0, 0), b2, voffB); PG8_STAGE(PG8_SB(0, 1), b2 + hstep, voffB); PG8_STAGE(PG8_SA(0, 0), a2, voffA);
;             PG8_WAIT_V(8); PG8_WAIT_L(0); PG8_BAR; PG8_MMA(1, 0, At, B0); PG8_MMA(1, 1, At, B1); PG8_BAR; PG8_SCHED;
.LBB0_187:
	s_ashr_i32 s75, s74, 31
	s_lshl_b64 s[36:37], s[74:75], 19
	s_add_u32 s78, s13, s36
	s_addc_u32 s79, s14, s37
	s_and_b64 s[36:37], s[4:5], exec
	s_cselect_b32 s34, s79, s83
	s_cselect_b32 s36, s78, s82
	s_ashr_i32 s77, s76, 31
	s_lshl_b64 s[42:43], s[76:77], 19
	s_add_u32 s80, s17, s42
	s_addc_u32 s81, s18, s43
	s_and_b64 s[42:43], s[4:5], exec
	s_cselect_b32 s37, s81, s85
	s_cselect_b32 s38, s80, s84
	s_add_u32 s40, s84, 0x100
	s_addc_u32 s42, s85, 0
	s_add_u32 s82, s82, 0x40080
	s_addc_u32 s83, s83, 0
	s_mov_b32 s43, -2
	s_waitcnt vmcnt(0)
	s_cmp_eq_u64 s[70:71], 0
	s_cbranch_scc1 .Lprio_up
	s_setprio 1
.Lprio_up:
	s_add_u32 s46, s82, 0xfffc0080
	s_addc_u32 s54, s83, -1
	s_add_i32 s55, 0, 0x10000
	s_cmp_eq_u32 s43, 12
	s_cselect_b32 s87, s34, s54
	s_cselect_b32 s86, s36, s46
	v_add_u32_e32 v149, s55, v146
	s_cselect_b32 s85, s37, s42
	s_cselect_b32 s84, s38, s40
	s_add_i32 s46, 0, 0x14000
	ds_read_b128 v[142:145], v149
	ds_read_b128 v[150:153], v149 offset:1024
	ds_read_b128 v[154:157], v149 offset:2048
	ds_read_b128 v[158:161], v149 offset:3072
	v_add_u32_e32 v149, s46, v146
	ds_read_b128 v[162:165], v149
	ds_read_b128 v[166:169], v149 offset:1024
	ds_read_b128 v[170:173], v149 offset:2048
	ds_read_b128 v[174:177], v149 offset:3072
	v_lshl_add_u64 v[194:195], s[82:83], 0, v[140:141]
	s_add_i32 m0, s20, 0xc000
	ds_read_b128 v[178:181], v148
	ds_read_b128 v[182:185], v148 offset:1024
	ds_read_b128 v[186:189], v148 offset:2048
	ds_read_b128 v[190:193], v148 offset:3072
	ds_read_b128 v[208:211], v148 offset:4096
	ds_read_b128 v[226:229], v148 offset:5120
	ds_read_b128 v[230:233], v148 offset:6144
	ds_read_b128 v[234:237], v148 offset:7168
	global_load_lds_dwordx4 v[194:195], off
	v_lshl_add_u64 v[194:195], s[82:83], 0, v[138:139]
	s_add_i32 m0, s20, 0xe000
	s_nop 0
	global_load_lds_dwordx4 v[194:195], off
	s_waitcnt vmcnt(8)
	s_waitcnt lgkmcnt(0)
	s_barrier
	s_waitcnt lgkmcnt(0)
	v_mfma_f32_16x16x32_bf16 v[126:129], v[142:145], v[178:181], 0
	v_mfma_f32_16x16x32_bf16 v[118:121], v[154:157], v[178:181], 0
	v_mfma_f32_16x16x32_bf16 v[110:113], v[142:145], v[186:189], 0
	v_mfma_f32_16x16x32_bf16 v[102:105], v[154:157], v[186:189], 0
	v_mfma_f32_16x16x32_bf16 v[94:97], v[142:145], v[208:211], 0
	v_mfma_f32_16x16x32_bf16 v[86:89], v[154:157], v[208:211], 0
	v_mfma_f32_16x16x32_bf16 v[78:81], v[142:145], v[230:233], 0
	v_mfma_f32_16x16x32_bf16 v[70:73], v[154:157], v[230:233], 0
	v_mfma_f32_16x16x32_bf16 v[126:129], v[150:153], v[182:185], v[126:129]
	v_mfma_f32_16x16x32_bf16 v[118:121], v[158:161], v[182:185], v[118:121]
	v_mfma_f32_16x16x32_bf16 v[110:113], v[150:153], v[190:193], v[110:113]
	v_mfma_f32_16x16x32_bf16 v[102:105], v[158:161], v[190:193], v[102:105]
	v_mfma_f32_16x16x32_bf16 v[94:97], v[150:153], v[226:229], v[94:97]
	v_mfma_f32_16x16x32_bf16 v[86:89], v[158:161], v[226:229], v[86:89]
	v_mfma_f32_16x16x32_bf16 v[78:81], v[150:153], v[234:237], v[78:81]
	v_mfma_f32_16x16x32_bf16 v[70:73], v[158:161], v[234:237], v[70:73]
	v_mfma_f32_16x16x32_bf16 v[130:133], v[162:165], v[178:181], 0
	v_mfma_f32_16x16x32_bf16 v[122:125], v[170:173], v[178:181], 0
	v_mfma_f32_16x16x32_bf16 v[114:117], v[162:165], v[186:189], 0
	v_mfma_f32_16x16x32_bf16 v[106:109], v[170:173], v[186:189], 0
	v_mfma_f32_16x16x32_bf16 v[98:101], v[162:165], v[208:211], 0
	v_mfma_f32_16x16x32_bf16 v[90:93], v[170:173], v[208:211], 0
	v_mfma_f32_16x16x32_bf16 v[82:85], v[162:165], v[230:233], 0
	v_mfma_f32_16x16x32_bf16 v[74:77], v[170:173], v[230:233], 0
	v_mfma_f32_16x16x32_bf16 v[130:133], v[166:169], v[182:185], v[130:133]
	v_mfma_f32_16x16x32_bf16 v[122:125], v[174:177], v[182:185], v[122:125]
	v_mfma_f32_16x16x32_bf16 v[114:117], v[166:169], v[190:193], v[114:117]
	v_mfma_f32_16x16x32_bf16 v[106:109], v[174:177], v[190:193], v[106:109]
	v_mfma_f32_16x16x32_bf16 v[98:101], v[166:169], v[226:229], v[98:101]
	v_mfma_f32_16x16x32_bf16 v[90:93], v[174:177], v[226:229], v[90:93]
	v_mfma_f32_16x16x32_bf16 v[82:85], v[166:169], v[234:237], v[82:85]
	v_mfma_f32_16x16x32_bf16 v[74:77], v[174:177], v[234:237], v[74:77]
	s_barrier
	s_add_i32 s54, s55, s19
	v_lshl_add_u64 v[194:195], s[84:85], 0, v[0:1]
	s_mov_b32 m0, s54
	ds_read_b128 v[178:181], v148 offset:16384
	ds_read_b128 v[182:185], v148 offset:17408
	ds_read_b128 v[186:189], v148 offset:18432
	ds_read_b128 v[190:193], v148 offset:19456
	ds_read_b128 v[208:211], v148 offset:20480
	ds_read_b128 v[226:229], v148 offset:21504
	ds_read_b128 v[230:233], v148 offset:22528
	ds_read_b128 v[234:237], v148 offset:23552
	global_load_lds_dwordx4 v[194:195], off
	s_add_i32 m0, s54, 0x2000
	s_add_u32 s54, s84, 0x40000
	v_lshl_add_u64 v[238:239], s[84:85], 0, v[2:3]
	s_addc_u32 s55, s85, 0
	s_add_i32 s46, s46, s19
	global_load_lds_dwordx4 v[238:239], off
	v_lshl_add_u64 v[240:241], s[54:55], 0, v[0:1]
	s_mov_b32 m0, s46
	v_lshl_add_u64 v[242:243], s[86:87], 0, v[134:135]
	global_load_lds_dwordx4 v[240:241], off
	v_lshl_add_u64 v[240:241], s[54:55], 0, v[2:3]
	s_add_i32 m0, s46, 0x2000
	s_nop 0
	global_load_lds_dwordx4 v[240:241], off
	v_lshl_add_u64 v[240:241], s[86:87], 0, v[136:137]
	s_mov_b32 m0, s20
	s_nop 0
	global_load_lds_dwordx4 v[240:241], off
	s_mov_b32 m0, s21
	s_nop 0
	global_load_lds_dwordx4 v[242:243], off
	s_waitcnt vmcnt(8)
	s_waitcnt lgkmcnt(0)
	s_barrier
; #define PG8_STAGE(bufoff, gbase, voff) do { _Pragma("unroll") for (int _i = 0; _i < 2; ++_i) \
;         __builtin_amdgcn_global_load_lds((const unsigned*)((const char*)(gbase) + (voff)[_i]), (PG8_LAS unsigned*)(lds + (bufoff) + ldsw + _i * 8192), 16, 0, 0); } while (0)
; #define PG8_LDA(dst, b, h) do { _Pragma("unroll") for (int m = 0; m < 4; ++m) _Pragma("unroll") for (int k = 0; k < 2; ++k) dst[m][k] = *(const PG8_LAS bf16x8*)(lds + PG8_SA(b, h) + aoff + m * 2048 + k * 1024); } while (0)
; #define PG8_LDB(dst, b, h) do { _Pragma("unroll") for (int n = 0; n < 2; ++n) _Pragma("unroll") for (int k = 0; k < 2; ++k) dst[n][k] = *(const PG8_LAS bf16x8*)(lds + PG8_SB(b, h) + boff + n * 2048 + k * 1024); } while (0)
; #define PG8_MMA(ai, bj, At, Bt) do { __builtin_amdgcn_s_setprio(1); _Pragma("unroll") for (int m = 0; m < 4; ++m) _Pragma("unroll") for (int n = 0; n < 2; ++n) _Pragma("unroll") for (int k = 0; k < 2; ++k) \
;         acc[ai][bj][m][n] = __builtin_amdgcn_mfma_f32_16x16x32_bf16(Bt[n][k], At[m][k], acc[ai][bj][m][n], 0, 0, 0); __builtin_amdgcn_s_setprio(0); } while (0)
; #define PG8_WAIT_V(n) asm volatile("s_waitcnt vmcnt(" #n ")" ::: "memory")
; #define PG8_WAIT_L(n) asm volatile("s_waitcnt lgkmcnt(" #n ")" ::: "memory")
; #define PG8_BAR __builtin_amdgcn_s_barrier()
; #define PG8_SCHED __builtin_amdgcn_sched_barrier(0)
; template <class Epi, class Sched, bool ALIGN_EPI = false, bool SP2 = false>
; __device__ __forceinline__ void gemm_phase(PG8_LAS unsigned char* lds, const Gemm g, const Sched& S, const Epi& E, const int tid) {
;     ...
;             PG8_WAIT_V(8); PG8_WAIT_L(0); PG8_BAR; PG8_MMA(1, 0, At, B0); PG8_MMA(1, 1, At, B1); PG8_BAR; PG8_SCHED;
;             PG8_LDB(B0, 1, 0); PG8_LDB(B1, 1, 1); PG8_SCHED; PG8_LDA(At, 1, 0); PG8_STAGE(PG8_SA(0, 1), a2 + hstep, voffA);
;             PG8_WAIT_V(8); PG8_WAIT_L(0); PG8_BAR; PG8_MMA(0, 0, At, B0); PG8_MMA(0, 1, At, B1); PG8_BAR; PG8_SCHED;
	s_waitcnt lgkmcnt(0)
	v_mfma_f32_16x16x32_bf16 v[62:65], v[142:145], v[178:181], 0
	v_mfma_f32_16x16x32_bf16 v[54:57], v[154:157], v[178:181], 0
	v_mfma_f32_16x16x32_bf16 v[46:49], v[142:145], v[186:189], 0
	v_mfma_f32_16x16x32_bf16 v[38:41], v[154:157], v[186:189], 0
	v_mfma_f32_16x16x32_bf16 v[30:33], v[142:145], v[208:211], 0
	v_mfma_f32_16x16x32_bf16 v[22:25], v[154:157], v[208:211], 0
	v_mfma_f32_16x16x32_bf16 v[14:17], v[142:145], v[230:233], 0
	v_mfma_f32_16x16x32_bf16 v[10:13], v[154:157], v[230:233], 0
	v_mfma_f32_16x16x32_bf16 v[62:65], v[150:153], v[182:185], v[62:65]
	v_mfma_f32_16x16x32_bf16 v[54:57], v[158:161], v[182:185], v[54:57]
	v_mfma_f32_16x16x32_bf16 v[46:49], v[150:153], v[190:193], v[46:49]
	v_mfma_f32_16x16x32_bf16 v[38:41], v[158:161], v[190:193], v[38:41]
	v_mfma_f32_16x16x32_bf16 v[30:33], v[150:153], v[226:229], v[30:33]
	v_mfma_f32_16x16x32_bf16 v[22:25], v[158:161], v[226:229], v[22:25]
	v_mfma_f32_16x16x32_bf16 v[14:17], v[150:153], v[234:237], v[14:17]
	v_mfma_f32_16x16x32_bf16 v[10:13], v[158:161], v[234:237], v[10:13]
	v_mfma_f32_16x16x32_bf16 v[66:69], v[162:165], v[178:181], 0
	v_mfma_f32_16x16x32_bf16 v[58:61], v[170:173], v[178:181], 0
	v_mfma_f32_16x16x32_bf16 v[50:53], v[162:165], v[186:189], 0
	v_mfma_f32_16x16x32_bf16 v[42:45], v[170:173], v[186:189], 0
	v_mfma_f32_16x16x32_bf16 v[34:37], v[162:165], v[208:211], 0
	v_mfma_f32_16x16x32_bf16 v[26:29], v[170:173], v[208:211], 0
	v_mfma_f32_16x16x32_bf16 v[18:21], v[162:165], v[230:233], 0
	v_mfma_f32_16x16x32_bf16 v[6:9], v[170:173], v[230:233], 0
	v_mfma_f32_16x16x32_bf16 v[66:69], v[166:169], v[182:185], v[66:69]
	v_mfma_f32_16x16x32_bf16 v[58:61], v[174:177], v[182:185], v[58:61]
	v_mfma_f32_16x16x32_bf16 v[50:53], v[166:169], v[190:193], v[50:53]
	v_mfma_f32_16x16x32_bf16 v[42:45], v[174:177], v[190:193], v[42:45]
	v_mfma_f32_16x16x32_bf16 v[34:37], v[166:169], v[226:229], v[34:37]
	v_mfma_f32_16x16x32_bf16 v[26:29], v[174:177], v[226:229], v[26:29]
	v_mfma_f32_16x16x32_bf16 v[18:21], v[166:169], v[234:237], v[18:21]
	v_mfma_f32_16x16x32_bf16 v[6:9], v[174:177], v[234:237], v[6:9]
	s_barrier
	s_add_i32 s46, 0, 0x18000
	v_add_u32_e32 v149, s46, v146
	s_add_i32 s75, 0, 0x1c000
	ds_read_b128 v[142:145], v149
	ds_read_b128 v[150:153], v149 offset:1024
	ds_read_b128 v[154:157], v149 offset:2048
	ds_read_b128 v[158:161], v149 offset:3072
	v_add_u32_e32 v149, s75, v146
	ds_read_b128 v[162:165], v149
	ds_read_b128 v[166:169], v149 offset:1024
	ds_read_b128 v[170:173], v149 offset:2048
	ds_read_b128 v[174:177], v149 offset:3072
	s_add_u32 s54, s86, 0x40000
	s_addc_u32 s55, s87, 0
	s_mov_b32 m0, s24
	v_lshl_add_u64 v[244:245], s[54:55], 0, v[136:137]
	ds_read_b128 v[178:181], v148 offset:32768
	ds_read_b128 v[182:185], v148 offset:33792
	ds_read_b128 v[186:189], v148 offset:34816
	ds_read_b128 v[190:193], v148 offset:35840
	ds_read_b128 v[208:211], v148 offset:36864
	ds_read_b128 v[226:229], v148 offset:37888
	ds_read_b128 v[230:233], v148 offset:38912
	ds_read_b128 v[234:237], v148 offset:39936
	global_load_lds_dwordx4 v[244:245], off
	v_lshl_add_u64 v[244:245], s[54:55], 0, v[134:135]
	s_mov_b32 m0, s25
	s_nop 0
	global_load_lds_dwordx4 v[244:245], off
	s_waitcnt vmcnt(8)
	s_waitcnt lgkmcnt(0)
	s_barrier
	s_waitcnt lgkmcnt(0)
	v_mfma_f32_16x16x32_bf16 v[126:129], v[142:145], v[178:181], v[126:129]
	v_mfma_f32_16x16x32_bf16 v[118:121], v[154:157], v[178:181], v[118:121]
	v_mfma_f32_16x16x32_bf16 v[110:113], v[142:145], v[186:189], v[110:113]
	v_mfma_f32_16x16x32_bf16 v[102:105], v[154:157], v[186:189], v[102:105]
	v_mfma_f32_16x16x32_bf16 v[94:97], v[142:145], v[208:211], v[94:97]
	v_mfma_f32_16x16x32_bf16 v[86:89], v[154:157], v[208:211], v[86:89]
	v_mfma_f32_16x16x32_bf16 v[78:81], v[142:145], v[230:233], v[78:81]
	v_mfma_f32_16x16x32_bf16 v[70:73], v[154:157], v[230:233], v[70:73]
	v_mfma_f32_16x16x32_bf16 v[126:129], v[150:153], v[182:185], v[126:129]
	v_mfma_f32_16x16x32_bf16 v[118:121], v[158:161], v[182:185], v[118:121]
	v_mfma_f32_16x16x32_bf16 v[110:113], v[150:153], v[190:193], v[110:113]
	v_mfma_f32_16x16x32_bf16 v[102:105], v[158:161], v[190:193], v[102:105]
	v_mfma_f32_16x16x32_bf16 v[94:97], v[150:153], v[226:229], v[94:97]
	v_mfma_f32_16x16x32_bf16 v[86:89], v[158:161], v[226:229], v[86:89]
	v_mfma_f32_16x16x32_bf16 v[78:81], v[150:153], v[234:237], v[78:81]
	v_mfma_f32_16x16x32_bf16 v[70:73], v[158:161], v[234:237], v[70:73]
	v_mfma_f32_16x16x32_bf16 v[130:133], v[162:165], v[178:181], v[130:133]
	v_mfma_f32_16x16x32_bf16 v[122:125], v[170:173], v[178:181], v[122:125]
	v_mfma_f32_16x16x32_bf16 v[114:117], v[162:165], v[186:189], v[114:117]
	v_mfma_f32_16x16x32_bf16 v[106:109], v[170:173], v[186:189], v[106:109]
	v_mfma_f32_16x16x32_bf16 v[98:101], v[162:165], v[208:211], v[98:101]
	v_mfma_f32_16x16x32_bf16 v[90:93], v[170:173], v[208:211], v[90:93]
	v_mfma_f32_16x16x32_bf16 v[82:85], v[162:165], v[230:233], v[82:85]
	v_mfma_f32_16x16x32_bf16 v[74:77], v[170:173], v[230:233], v[74:77]
	v_mfma_f32_16x16x32_bf16 v[130:133], v[166:169], v[182:185], v[130:133]
	v_mfma_f32_16x16x32_bf16 v[122:125], v[174:177], v[182:185], v[122:125]
	v_mfma_f32_16x16x32_bf16 v[114:117], v[166:169], v[190:193], v[114:117]
	v_mfma_f32_16x16x32_bf16 v[106:109], v[174:177], v[190:193], v[106:109]
	v_mfma_f32_16x16x32_bf16 v[98:101], v[166:169], v[226:229], v[98:101]
	v_mfma_f32_16x16x32_bf16 v[90:93], v[174:177], v[226:229], v[90:93]
	v_mfma_f32_16x16x32_bf16 v[82:85], v[166:169], v[234:237], v[82:85]
	v_mfma_f32_16x16x32_bf16 v[74:77], v[174:177], v[234:237], v[74:77]
	s_barrier
; #define PG8_STAGE(bufoff, gbase, voff) do { _Pragma("unroll") for (int _i = 0; _i < 2; ++_i) \
;         __builtin_amdgcn_global_load_lds((const unsigned*)((const char*)(gbase) + (voff)[_i]), (PG8_LAS unsigned*)(lds + (bufoff) + ldsw + _i * 8192), 16, 0, 0); } while (0)
; #define PG8_LDA(dst, b, h) do { _Pragma("unroll") for (int m = 0; m < 4; ++m) _Pragma("unroll") for (int k = 0; k < 2; ++k) dst[m][k] = *(const PG8_LAS bf16x8*)(lds + PG8_SA(b, h) + aoff + m * 2048 + k * 1024); } while (0)
; #define PG8_LDB(dst, b, h) do { _Pragma("unroll") for (int n = 0; n < 2; ++n) _Pragma("unroll") for (int k = 0; k < 2; ++k) dst[n][k] = *(const PG8_LAS bf16x8*)(lds + PG8_SB(b, h) + boff + n * 2048 + k * 1024); } while (0)
; #define PG8_MMA(ai, bj, At, Bt) do { __builtin_amdgcn_s_setprio(1); _Pragma("unroll") for (int m = 0; m < 4; ++m) _Pragma("unroll") for (int n = 0; n < 2; ++n) _Pragma("unroll") for (int k = 0; k < 2; ++k) \
;         acc[ai][bj][m][n] = __builtin_amdgcn_mfma_f32_16x16x32_bf16(Bt[n][k], At[m][k], acc[ai][bj][m][n], 0, 0, 0); __builtin_amdgcn_s_setprio(0); } while (0)
; #define PG8_WAIT_V(n) asm volatile("s_waitcnt vmcnt(" #n ")" ::: "memory")
; #define PG8_WAIT_L(n) asm volatile("s_waitcnt lgkmcnt(" #n ")" ::: "memory")
; #define PG8_BAR __builtin_amdgcn_s_barrier()
; #define PG8_SCHED __builtin_amdgcn_sched_barrier(0)
; template <class Epi, class Sched, bool ALIGN_EPI = false, bool SP2 = false>
; __device__ __forceinline__ void gemm_phase(PG8_LAS unsigned char* lds, const Gemm g, const Sched& S, const Epi& E, const int tid) {
;     ...
;             PG8_LDB(B0, 0, 0); PG8_LDB(B1, 0, 1); PG8_SCHED; PG8_LDA(At, 0, 0); PG8_STAGE(PG8_SA(1, 1), a1 + hstep, voffA);
;     ...
;             PG8_LDA(At, 1, 1); PG8_STAGE(PG8_SB(1, 0), b3, voffB); PG8_STAGE(PG8_SB(1, 1), b3 + hstep, voffB); PG8_STAGE(PG8_SA(1, 0), a3, voffA);
;             PG8_WAIT_V(8); PG8_WAIT_L(0); PG8_BAR; PG8_MMA(1, 0, At, B0); PG8_MMA(1, 1, At, B1); PG8_BAR; PG8_SCHED;
	s_add_i32 s46, s46, s19
	v_lshl_add_u64 v[194:195], v[194:195], 0, s[50:51]
	s_mov_b32 m0, s46
	ds_read_b128 v[178:181], v148 offset:49152
	ds_read_b128 v[182:185], v148 offset:50176
	ds_read_b128 v[186:189], v148 offset:51200
	ds_read_b128 v[190:193], v148 offset:52224
	ds_read_b128 v[208:211], v148 offset:53248
	ds_read_b128 v[226:229], v148 offset:54272
	ds_read_b128 v[230:233], v148 offset:55296
	ds_read_b128 v[234:237], v148 offset:56320
	global_load_lds_dwordx4 v[194:195], off
	s_add_i32 m0, s46, 0x2000
	s_add_u32 s54, s84, 0x40080
	v_lshl_add_u64 v[194:195], v[238:239], 0, s[50:51]
	s_addc_u32 s55, s85, 0
	s_add_i32 s46, s75, s19
	global_load_lds_dwordx4 v[194:195], off
	v_lshl_add_u64 v[194:195], s[54:55], 0, v[0:1]
	s_mov_b32 m0, s46
	s_nop 0
	global_load_lds_dwordx4 v[194:195], off
	v_lshl_add_u64 v[194:195], s[54:55], 0, v[2:3]
	s_add_i32 m0, s46, 0x2000
	s_nop 0
	global_load_lds_dwordx4 v[194:195], off
	v_lshl_add_u64 v[194:195], v[240:241], 0, s[50:51]
	s_mov_b32 m0, s28
	s_nop 0
	global_load_lds_dwordx4 v[194:195], off
	v_lshl_add_u64 v[194:195], v[242:243], 0, s[50:51]
	s_mov_b32 m0, s30
	s_nop 0
	global_load_lds_dwordx4 v[194:195], off
	s_waitcnt vmcnt(8)
	s_waitcnt lgkmcnt(0)
	s_barrier
	s_waitcnt lgkmcnt(0)
	v_mfma_f32_16x16x32_bf16 v[62:65], v[142:145], v[178:181], v[62:65]
	v_mfma_f32_16x16x32_bf16 v[54:57], v[154:157], v[178:181], v[54:57]
	v_mfma_f32_16x16x32_bf16 v[46:49], v[142:145], v[186:189], v[46:49]
	v_mfma_f32_16x16x32_bf16 v[38:41], v[154:157], v[186:189], v[38:41]
	v_mfma_f32_16x16x32_bf16 v[30:33], v[142:145], v[208:211], v[30:33]
	v_mfma_f32_16x16x32_bf16 v[22:25], v[154:157], v[208:211], v[22:25]
	v_mfma_f32_16x16x32_bf16 v[14:17], v[142:145], v[230:233], v[14:17]
	v_mfma_f32_16x16x32_bf16 v[10:13], v[154:157], v[230:233], v[10:13]
	v_mfma_f32_16x16x32_bf16 v[62:65], v[150:153], v[182:185], v[62:65]
	v_mfma_f32_16x16x32_bf16 v[54:57], v[158:161], v[182:185], v[54:57]
	v_mfma_f32_16x16x32_bf16 v[46:49], v[150:153], v[190:193], v[46:49]
	v_mfma_f32_16x16x32_bf16 v[38:41], v[158:161], v[190:193], v[38:41]
	v_mfma_f32_16x16x32_bf16 v[30:33], v[150:153], v[226:229], v[30:33]
	v_mfma_f32_16x16x32_bf16 v[22:25], v[158:161], v[226:229], v[22:25]
	v_mfma_f32_16x16x32_bf16 v[14:17], v[150:153], v[234:237], v[14:17]
	v_mfma_f32_16x16x32_bf16 v[10:13], v[158:161], v[234:237], v[10:13]
	v_mfma_f32_16x16x32_bf16 v[66:69], v[162:165], v[178:181], v[66:69]
	v_mfma_f32_16x16x32_bf16 v[58:61], v[170:173], v[178:181], v[58:61]
	v_mfma_f32_16x16x32_bf16 v[50:53], v[162:165], v[186:189], v[50:53]
	v_mfma_f32_16x16x32_bf16 v[42:45], v[170:173], v[186:189], v[42:45]
	v_mfma_f32_16x16x32_bf16 v[34:37], v[162:165], v[208:211], v[34:37]
	v_mfma_f32_16x16x32_bf16 v[26:29], v[170:173], v[208:211], v[26:29]
	v_mfma_f32_16x16x32_bf16 v[18:21], v[162:165], v[230:233], v[18:21]
	v_mfma_f32_16x16x32_bf16 v[6:9], v[170:173], v[230:233], v[6:9]
	v_mfma_f32_16x16x32_bf16 v[66:69], v[166:169], v[182:185], v[66:69]
	v_mfma_f32_16x16x32_bf16 v[58:61], v[174:177], v[182:185], v[58:61]
	v_mfma_f32_16x16x32_bf16 v[50:53], v[166:169], v[190:193], v[50:53]
	v_mfma_f32_16x16x32_bf16 v[42:45], v[174:177], v[190:193], v[42:45]
	v_mfma_f32_16x16x32_bf16 v[34:37], v[166:169], v[226:229], v[34:37]
	v_mfma_f32_16x16x32_bf16 v[26:29], v[174:177], v[226:229], v[26:29]
	v_mfma_f32_16x16x32_bf16 v[18:21], v[166:169], v[234:237], v[18:21]
	v_mfma_f32_16x16x32_bf16 v[6:9], v[174:177], v[234:237], v[6:9]
	s_barrier
	s_add_i32 s43, s43, 2
	s_add_u32 s40, s40, 0x100
	s_addc_u32 s42, s42, 0
	s_add_u32 s82, s82, 0x100
	s_addc_u32 s83, s83, 0
	s_cmp_gt_u32 s43, 13
.LBB0_188:
	s_add_u32 s46, s82, 0xfffc0080
	s_addc_u32 s54, s83, -1
	s_add_i32 s55, 0, 0x10000
	s_cmp_eq_u32 s43, 12
	s_cselect_b32 s87, s34, s54
	s_cselect_b32 s86, s36, s46
	v_add_u32_e32 v149, s55, v146
	s_cselect_b32 s85, s37, s42
	s_cselect_b32 s84, s38, s40
	s_add_i32 s46, 0, 0x14000
	ds_read_b128 v[142:145], v149
	ds_read_b128 v[150:153], v149 offset:1024
	ds_read_b128 v[154:157], v149 offset:2048
	ds_read_b128 v[158:161], v149 offset:3072
	v_add_u32_e32 v149, s46, v146
	ds_read_b128 v[162:165], v149
	ds_read_b128 v[166:169], v149 offset:1024
	ds_read_b128 v[170:173], v149 offset:2048
	ds_read_b128 v[174:177], v149 offset:3072
	v_lshl_add_u64 v[194:195], s[82:83], 0, v[140:141]
	s_add_i32 m0, s20, 0xc000
	ds_read_b128 v[178:181], v148
	ds_read_b128 v[182:185], v148 offset:1024
	ds_read_b128 v[186:189], v148 offset:2048
	ds_read_b128 v[190:193], v148 offset:3072
	ds_read_b128 v[208:211], v148 offset:4096
	ds_read_b128 v[226:229], v148 offset:5120
	ds_read_b128 v[230:233], v148 offset:6144
	ds_read_b128 v[234:237], v148 offset:7168
	global_load_lds_dwordx4 v[194:195], off
	v_lshl_add_u64 v[194:195], s[82:83], 0, v[138:139]
	s_add_i32 m0, s20, 0xe000
	s_nop 0
	global_load_lds_dwordx4 v[194:195], off
	s_waitcnt vmcnt(8)
	s_waitcnt lgkmcnt(0)
	s_barrier
; #define PG8_STAGE(bufoff, gbase, voff) do { _Pragma("unroll") for (int _i = 0; _i < 2; ++_i) \
;         __builtin_amdgcn_global_load_lds((const unsigned*)((const char*)(gbase) + (voff)[_i]), (PG8_LAS unsigned*)(lds + (bufoff) + ldsw + _i * 8192), 16, 0, 0); } while (0)
; #define PG8_LDA(dst, b, h) do { _Pragma("unroll") for (int m = 0; m < 4; ++m) _Pragma("unroll") for (int k = 0; k < 2; ++k) dst[m][k] = *(const PG8_LAS bf16x8*)(lds + PG8_SA(b, h) + aoff + m * 2048 + k * 1024); } while (0)
; #define PG8_LDB(dst, b, h) do { _Pragma("unroll") for (int n = 0; n < 2; ++n) _Pragma("unroll") for (int k = 0; k < 2; ++k) dst[n][k] = *(const PG8_LAS bf16x8*)(lds + PG8_SB(b, h) + boff + n * 2048 + k * 1024); } while (0)
; #define PG8_MMA(ai, bj, At, Bt) do { __builtin_amdgcn_s_setprio(1); _Pragma("unroll") for (int m = 0; m < 4; ++m) _Pragma("unroll") for (int n = 0; n < 2; ++n) _Pragma("unroll") for (int k = 0; k < 2; ++k) \
;         acc[ai][bj][m][n] = __builtin_amdgcn_mfma_f32_16x16x32_bf16(Bt[n][k], At[m][k], acc[ai][bj][m][n], 0, 0, 0); __builtin_amdgcn_s_setprio(0); } while (0)
; #define PG8_WAIT_V(n) asm volatile("s_waitcnt vmcnt(" #n ")" ::: "memory")
; #define PG8_WAIT_L(n) asm volatile("s_waitcnt lgkmcnt(" #n ")" ::: "memory")
; #define PG8_BAR __builtin_amdgcn_s_barrier()
; #define PG8_SCHED __builtin_amdgcn_sched_barrier(0)
; template <class Epi, class Sched, bool ALIGN_EPI = false, bool SP2 = false>
; __device__ __forceinline__ void gemm_phase(PG8_LAS unsigned char* lds, const Gemm g, const Sched& S, const Epi& E, const int tid) {
;     ...
;             PG8_WAIT_V(8); PG8_WAIT_L(0); PG8_BAR; PG8_MMA(0, 0, At, B0); PG8_MMA(0, 1, At, B1); PG8_BAR; PG8_SCHED;
;             PG8_LDA(At, 0, 1); PG8_STAGE(PG8_SB(0, 0), b2, voffB); PG8_STAGE(PG8_SB(0, 1), b2 + hstep, voffB); PG8_STAGE(PG8_SA(0, 0), a2, voffA);
;             PG8_WAIT_V(8); PG8_WAIT_L(0); PG8_BAR; PG8_MMA(1, 0, At, B0); PG8_MMA(1, 1, At, B1); PG8_BAR; PG8_SCHED;
;             PG8_LDB(B0, 1, 0); PG8_LDB(B1, 1, 1); PG8_SCHED; PG8_LDA(At, 1, 0); PG8_STAGE(PG8_SA(0, 1), a2 + hstep, voffA);
	s_waitcnt lgkmcnt(0)
	v_mfma_f32_16x16x32_bf16 v[126:129], v[142:145], v[178:181], v[126:129]
	v_mfma_f32_16x16x32_bf16 v[118:121], v[154:157], v[178:181], v[118:121]
	v_mfma_f32_16x16x32_bf16 v[110:113], v[142:145], v[186:189], v[110:113]
	v_mfma_f32_16x16x32_bf16 v[102:105], v[154:157], v[186:189], v[102:105]
	v_mfma_f32_16x16x32_bf16 v[94:97], v[142:145], v[208:211], v[94:97]
	v_mfma_f32_16x16x32_bf16 v[86:89], v[154:157], v[208:211], v[86:89]
	v_mfma_f32_16x16x32_bf16 v[78:81], v[142:145], v[230:233], v[78:81]
	v_mfma_f32_16x16x32_bf16 v[70:73], v[154:157], v[230:233], v[70:73]
	v_mfma_f32_16x16x32_bf16 v[126:129], v[150:153], v[182:185], v[126:129]
	v_mfma_f32_16x16x32_bf16 v[118:121], v[158:161], v[182:185], v[118:121]
	v_mfma_f32_16x16x32_bf16 v[110:113], v[150:153], v[190:193], v[110:113]
	v_mfma_f32_16x16x32_bf16 v[102:105], v[158:161], v[190:193], v[102:105]
	v_mfma_f32_16x16x32_bf16 v[94:97], v[150:153], v[226:229], v[94:97]
	v_mfma_f32_16x16x32_bf16 v[86:89], v[158:161], v[226:229], v[86:89]
	v_mfma_f32_16x16x32_bf16 v[78:81], v[150:153], v[234:237], v[78:81]
	v_mfma_f32_16x16x32_bf16 v[70:73], v[158:161], v[234:237], v[70:73]
	v_mfma_f32_16x16x32_bf16 v[130:133], v[162:165], v[178:181], v[130:133]
	v_mfma_f32_16x16x32_bf16 v[122:125], v[170:173], v[178:181], v[122:125]
	v_mfma_f32_16x16x32_bf16 v[114:117], v[162:165], v[186:189], v[114:117]
	v_mfma_f32_16x16x32_bf16 v[106:109], v[170:173], v[186:189], v[106:109]
	v_mfma_f32_16x16x32_bf16 v[98:101], v[162:165], v[208:211], v[98:101]
	v_mfma_f32_16x16x32_bf16 v[90:93], v[170:173], v[208:211], v[90:93]
	v_mfma_f32_16x16x32_bf16 v[82:85], v[162:165], v[230:233], v[82:85]
	v_mfma_f32_16x16x32_bf16 v[74:77], v[170:173], v[230:233], v[74:77]
	v_mfma_f32_16x16x32_bf16 v[130:133], v[166:169], v[182:185], v[130:133]
	v_mfma_f32_16x16x32_bf16 v[122:125], v[174:177], v[182:185], v[122:125]
	v_mfma_f32_16x16x32_bf16 v[114:117], v[166:169], v[190:193], v[114:117]
	v_mfma_f32_16x16x32_bf16 v[106:109], v[174:177], v[190:193], v[106:109]
	v_mfma_f32_16x16x32_bf16 v[98:101], v[166:169], v[226:229], v[98:101]
	v_mfma_f32_16x16x32_bf16 v[90:93], v[174:177], v[226:229], v[90:93]
	v_mfma_f32_16x16x32_bf16 v[82:85], v[166:169], v[234:237], v[82:85]
	v_mfma_f32_16x16x32_bf16 v[74:77], v[174:177], v[234:237], v[74:77]
	s_barrier
	s_add_i32 s54, s55, s19
	v_lshl_add_u64 v[194:195], s[84:85], 0, v[0:1]
	s_mov_b32 m0, s54
	ds_read_b128 v[178:181], v148 offset:16384
	ds_read_b128 v[182:185], v148 offset:17408
	ds_read_b128 v[186:189], v148 offset:18432
	ds_read_b128 v[190:193], v148 offset:19456
	ds_read_b128 v[208:211], v148 offset:20480
	ds_read_b128 v[226:229], v148 offset:21504
	ds_read_b128 v[230:233], v148 offset:22528
	ds_read_b128 v[234:237], v148 offset:23552
	global_load_lds_dwordx4 v[194:195], off
	s_add_i32 m0, s54, 0x2000
	s_add_u32 s54, s84, 0x40000
	v_lshl_add_u64 v[238:239], s[84:85], 0, v[2:3]
	s_addc_u32 s55, s85, 0
	s_add_i32 s46, s46, s19
	global_load_lds_dwordx4 v[238:239], off
	v_lshl_add_u64 v[240:241], s[54:55], 0, v[0:1]
	s_mov_b32 m0, s46
	v_lshl_add_u64 v[242:243], s[86:87], 0, v[134:135]
	global_load_lds_dwordx4 v[240:241], off
	v_lshl_add_u64 v[240:241], s[54:55], 0, v[2:3]
	s_add_i32 m0, s46, 0x2000
	s_nop 0
	global_load_lds_dwordx4 v[240:241], off
	v_lshl_add_u64 v[240:241], s[86:87], 0, v[136:137]
	s_mov_b32 m0, s20
	s_nop 0
	global_load_lds_dwordx4 v[240:241], off
	s_mov_b32 m0, s21
	s_nop 0
	global_load_lds_dwordx4 v[242:243], off
	s_waitcnt vmcnt(8)
	s_waitcnt lgkmcnt(0)
	s_barrier
	s_waitcnt lgkmcnt(0)
	v_mfma_f32_16x16x32_bf16 v[62:65], v[142:145], v[178:181], v[62:65]
	v_mfma_f32_16x16x32_bf16 v[54:57], v[154:157], v[178:181], v[54:57]
	v_mfma_f32_16x16x32_bf16 v[46:49], v[142:145], v[186:189], v[46:49]
	v_mfma_f32_16x16x32_bf16 v[38:41], v[154:157], v[186:189], v[38:41]
	v_mfma_f32_16x16x32_bf16 v[30:33], v[142:145], v[208:211], v[30:33]
	v_mfma_f32_16x16x32_bf16 v[22:25], v[154:157], v[208:211], v[22:25]
	v_mfma_f32_16x16x32_bf16 v[14:17], v[142:145], v[230:233], v[14:17]
	v_mfma_f32_16x16x32_bf16 v[10:13], v[154:157], v[230:233], v[10:13]
	v_mfma_f32_16x16x32_bf16 v[62:65], v[150:153], v[182:185], v[62:65]
	v_mfma_f32_16x16x32_bf16 v[54:57], v[158:161], v[182:185], v[54:57]
	v_mfma_f32_16x16x32_bf16 v[46:49], v[150:153], v[190:193], v[46:49]
	v_mfma_f32_16x16x32_bf16 v[38:41], v[158:161], v[190:193], v[38:41]
	v_mfma_f32_16x16x32_bf16 v[30:33], v[150:153], v[226:229], v[30:33]
	v_mfma_f32_16x16x32_bf16 v[22:25], v[158:161], v[226:229], v[22:25]
	v_mfma_f32_16x16x32_bf16 v[14:17], v[150:153], v[234:237], v[14:17]
	v_mfma_f32_16x16x32_bf16 v[10:13], v[158:161], v[234:237], v[10:13]
	v_mfma_f32_16x16x32_bf16 v[66:69], v[162:165], v[178:181], v[66:69]
	v_mfma_f32_16x16x32_bf16 v[58:61], v[170:173], v[178:181], v[58:61]
	v_mfma_f32_16x16x32_bf16 v[50:53], v[162:165], v[186:189], v[50:53]
	v_mfma_f32_16x16x32_bf16 v[42:45], v[170:173], v[186:189], v[42:45]
	v_mfma_f32_16x16x32_bf16 v[34:37], v[162:165], v[208:211], v[34:37]
	v_mfma_f32_16x16x32_bf16 v[26:29], v[170:173], v[208:211], v[26:29]
	v_mfma_f32_16x16x32_bf16 v[18:21], v[162:165], v[230:233], v[18:21]
	v_mfma_f32_16x16x32_bf16 v[6:9], v[170:173], v[230:233], v[6:9]
	v_mfma_f32_16x16x32_bf16 v[66:69], v[166:169], v[182:185], v[66:69]
	v_mfma_f32_16x16x32_bf16 v[58:61], v[174:177], v[182:185], v[58:61]
	v_mfma_f32_16x16x32_bf16 v[50:53], v[166:169], v[190:193], v[50:53]
	v_mfma_f32_16x16x32_bf16 v[42:45], v[174:177], v[190:193], v[42:45]
	v_mfma_f32_16x16x32_bf16 v[34:37], v[166:169], v[226:229], v[34:37]
	v_mfma_f32_16x16x32_bf16 v[26:29], v[174:177], v[226:229], v[26:29]
	v_mfma_f32_16x16x32_bf16 v[18:21], v[166:169], v[234:237], v[18:21]
	v_mfma_f32_16x16x32_bf16 v[6:9], v[174:177], v[234:237], v[6:9]
	s_barrier
; #define PG8_STAGE(bufoff, gbase, voff) do { _Pragma("unroll") for (int _i = 0; _i < 2; ++_i) \
;         __builtin_amdgcn_global_load_lds((const unsigned*)((const char*)(gbase) + (voff)[_i]), (PG8_LAS unsigned*)(lds + (bufoff) + ldsw + _i * 8192), 16, 0, 0); } while (0)
; #define PG8_LDA(dst, b, h) do { _Pragma("unroll") for (int m = 0; m < 4; ++m) _Pragma("unroll") for (int k = 0; k < 2; ++k) dst[m][k] = *(const PG8_LAS bf16x8*)(lds + PG8_SA(b, h) + aoff + m * 2048 + k * 1024); } while (0)
; #define PG8_LDB(dst, b, h) do { _Pragma("unroll") for (int n = 0; n < 2; ++n) _Pragma("unroll") for (int k = 0; k < 2; ++k) dst[n][k] = *(const PG8_LAS bf16x8*)(lds + PG8_SB(b, h) + boff + n * 2048 + k * 1024); } while (0)
; #define PG8_MMA(ai, bj, At, Bt) do { __builtin_amdgcn_s_setprio(1); _Pragma("unroll") for (int m = 0; m < 4; ++m) _Pragma("unroll") for (int n = 0; n < 2; ++n) _Pragma("unroll") for (int k = 0; k < 2; ++k) \
;         acc[ai][bj][m][n] = __builtin_amdgcn_mfma_f32_16x16x32_bf16(Bt[n][k], At[m][k], acc[ai][bj][m][n], 0, 0, 0); __builtin_amdgcn_s_setprio(0); } while (0)
; #define PG8_WAIT_V(n) asm volatile("s_waitcnt vmcnt(" #n ")" ::: "memory")
; #define PG8_WAIT_L(n) asm volatile("s_waitcnt lgkmcnt(" #n ")" ::: "memory")
; #define PG8_BAR __builtin_amdgcn_s_barrier()
; #define PG8_SCHED __builtin_amdgcn_sched_barrier(0)
; template <class Epi, class Sched, bool ALIGN_EPI = false, bool SP2 = false>
; __device__ __forceinline__ void gemm_phase(PG8_LAS unsigned char* lds, const Gemm g, const Sched& S, const Epi& E, const int tid) {
;     ...
;             PG8_LDB(B0, 1, 0); PG8_LDB(B1, 1, 1); PG8_SCHED; PG8_LDA(At, 1, 0); PG8_STAGE(PG8_SA(0, 1), a2 + hstep, voffA);
;             PG8_WAIT_V(8); PG8_WAIT_L(0); PG8_BAR; PG8_MMA(0, 0, At, B0); PG8_MMA(0, 1, At, B1); PG8_BAR; PG8_SCHED;
;             PG8_LDA(At, 1, 1); PG8_STAGE(PG8_SB(1, 0), b3, voffB); PG8_STAGE(PG8_SB(1, 1), b3 + hstep, voffB); PG8_STAGE(PG8_SA(1, 0), a3, voffA);
;             PG8_WAIT_V(8); PG8_WAIT_L(0); PG8_BAR; PG8_MMA(1, 0, At, B0); PG8_MMA(1, 1, At, B1); PG8_BAR; PG8_SCHED;
	s_add_i32 s46, 0, 0x18000
	v_add_u32_e32 v149, s46, v146
	s_add_i32 s75, 0, 0x1c000
	ds_read_b128 v[142:145], v149
	ds_read_b128 v[150:153], v149 offset:1024
	ds_read_b128 v[154:157], v149 offset:2048
	ds_read_b128 v[158:161], v149 offset:3072
	v_add_u32_e32 v149, s75, v146
	ds_read_b128 v[162:165], v149
	ds_read_b128 v[166:169], v149 offset:1024
	ds_read_b128 v[170:173], v149 offset:2048
	ds_read_b128 v[174:177], v149 offset:3072
	s_add_u32 s54, s86, 0x40000
	s_addc_u32 s55, s87, 0
	s_mov_b32 m0, s24
	v_lshl_add_u64 v[244:245], s[54:55], 0, v[136:137]
	ds_read_b128 v[178:181], v148 offset:32768
	ds_read_b128 v[182:185], v148 offset:33792
	ds_read_b128 v[186:189], v148 offset:34816
	ds_read_b128 v[190:193], v148 offset:35840
	ds_read_b128 v[208:211], v148 offset:36864
	ds_read_b128 v[226:229], v148 offset:37888
	ds_read_b128 v[230:233], v148 offset:38912
	ds_read_b128 v[234:237], v148 offset:39936
	global_load_lds_dwordx4 v[244:245], off
	v_lshl_add_u64 v[244:245], s[54:55], 0, v[134:135]
	s_mov_b32 m0, s25
	s_nop 0
	global_load_lds_dwordx4 v[244:245], off
	s_waitcnt vmcnt(8)
	s_waitcnt lgkmcnt(0)
	s_barrier
	s_waitcnt lgkmcnt(0)
	v_mfma_f32_16x16x32_bf16 v[126:129], v[142:145], v[178:181], v[126:129]
	v_mfma_f32_16x16x32_bf16 v[118:121], v[154:157], v[178:181], v[118:121]
	v_mfma_f32_16x16x32_bf16 v[110:113], v[142:145], v[186:189], v[110:113]
	v_mfma_f32_16x16x32_bf16 v[102:105], v[154:157], v[186:189], v[102:105]
	v_mfma_f32_16x16x32_bf16 v[94:97], v[142:145], v[208:211], v[94:97]
	v_mfma_f32_16x16x32_bf16 v[86:89], v[154:157], v[208:211], v[86:89]
	v_mfma_f32_16x16x32_bf16 v[78:81], v[142:145], v[230:233], v[78:81]
	v_mfma_f32_16x16x32_bf16 v[70:73], v[154:157], v[230:233], v[70:73]
	v_mfma_f32_16x16x32_bf16 v[126:129], v[150:153], v[182:185], v[126:129]
	v_mfma_f32_16x16x32_bf16 v[118:121], v[158:161], v[182:185], v[118:121]
	v_mfma_f32_16x16x32_bf16 v[110:113], v[150:153], v[190:193], v[110:113]
	v_mfma_f32_16x16x32_bf16 v[102:105], v[158:161], v[190:193], v[102:105]
	v_mfma_f32_16x16x32_bf16 v[94:97], v[150:153], v[226:229], v[94:97]
	v_mfma_f32_16x16x32_bf16 v[86:89], v[158:161], v[226:229], v[86:89]
	v_mfma_f32_16x16x32_bf16 v[78:81], v[150:153], v[234:237], v[78:81]
	v_mfma_f32_16x16x32_bf16 v[70:73], v[158:161], v[234:237], v[70:73]
	v_mfma_f32_16x16x32_bf16 v[130:133], v[162:165], v[178:181], v[130:133]
	v_mfma_f32_16x16x32_bf16 v[122:125], v[170:173], v[178:181], v[122:125]
	v_mfma_f32_16x16x32_bf16 v[114:117], v[162:165], v[186:189], v[114:117]
	v_mfma_f32_16x16x32_bf16 v[106:109], v[170:173], v[186:189], v[106:109]
	v_mfma_f32_16x16x32_bf16 v[98:101], v[162:165], v[208:211], v[98:101]
	v_mfma_f32_16x16x32_bf16 v[90:93], v[170:173], v[208:211], v[90:93]
	v_mfma_f32_16x16x32_bf16 v[82:85], v[162:165], v[230:233], v[82:85]
	v_mfma_f32_16x16x32_bf16 v[74:77], v[170:173], v[230:233], v[74:77]
	v_mfma_f32_16x16x32_bf16 v[130:133], v[166:169], v[182:185], v[130:133]
	v_mfma_f32_16x16x32_bf16 v[122:125], v[174:177], v[182:185], v[122:125]
	v_mfma_f32_16x16x32_bf16 v[114:117], v[166:169], v[190:193], v[114:117]
	v_mfma_f32_16x16x32_bf16 v[106:109], v[174:177], v[190:193], v[106:109]
	v_mfma_f32_16x16x32_bf16 v[98:101], v[166:169], v[226:229], v[98:101]
	v_mfma_f32_16x16x32_bf16 v[90:93], v[174:177], v[226:229], v[90:93]
	v_mfma_f32_16x16x32_bf16 v[82:85], v[166:169], v[234:237], v[82:85]
	v_mfma_f32_16x16x32_bf16 v[74:77], v[174:177], v[234:237], v[74:77]
	s_barrier
	s_add_i32 s46, s46, s19
	v_lshl_add_u64 v[194:195], v[194:195], 0, s[50:51]
	s_mov_b32 m0, s46
	ds_read_b128 v[178:181], v148 offset:49152
	ds_read_b128 v[182:185], v148 offset:50176
	ds_read_b128 v[186:189], v148 offset:51200
	ds_read_b128 v[190:193], v148 offset:52224
	ds_read_b128 v[208:211], v148 offset:53248
	ds_read_b128 v[226:229], v148 offset:54272
	ds_read_b128 v[230:233], v148 offset:55296
	ds_read_b128 v[234:237], v148 offset:56320
	global_load_lds_dwordx4 v[194:195], off
	s_add_i32 m0, s46, 0x2000
	s_add_u32 s54, s84, 0x40080
	v_lshl_add_u64 v[194:195], v[238:239], 0, s[50:51]
	s_addc_u32 s55, s85, 0
	s_add_i32 s46, s75, s19
	global_load_lds_dwordx4 v[194:195], off
	v_lshl_add_u64 v[194:195], s[54:55], 0, v[0:1]
	s_mov_b32 m0, s46
	s_nop 0
	global_load_lds_dwordx4 v[194:195], off
	v_lshl_add_u64 v[194:195], s[54:55], 0, v[2:3]
	s_add_i32 m0, s46, 0x2000
	s_nop 0
	global_load_lds_dwordx4 v[194:195], off
	v_lshl_add_u64 v[194:195], v[240:241], 0, s[50:51]
	s_mov_b32 m0, s28
	s_nop 0
	global_load_lds_dwordx4 v[194:195], off
	v_lshl_add_u64 v[194:195], v[242:243], 0, s[50:51]
	s_mov_b32 m0, s30
	s_nop 0
	global_load_lds_dwordx4 v[194:195], off
	s_waitcnt vmcnt(8)
	s_waitcnt lgkmcnt(0)
	s_barrier
; #define PG8_GAS __attribute__((address_space(1)))
; __device__ __forceinline__ unsigned cvtpk(float lo, float hi) { f32x2 v = {lo, hi}; bf16x2_t b = __builtin_convertvector(v, bf16x2_t); return __builtin_bit_cast(unsigned, b); }
; __device__ __forceinline__ float silu_mul(float g, float u) { return g * u * __builtin_amdgcn_rcpf(1.0f + __builtin_amdgcn_exp2f(-1.4426950408889634f * g)); }
; #define PG8_MMA(ai, bj, At, Bt) do { __builtin_amdgcn_s_setprio(1); _Pragma("unroll") for (int m = 0; m < 4; ++m) _Pragma("unroll") for (int n = 0; n < 2; ++n) _Pragma("unroll") for (int k = 0; k < 2; ++k) \
;         acc[ai][bj][m][n] = __builtin_amdgcn_mfma_f32_16x16x32_bf16(Bt[n][k], At[m][k], acc[ai][bj][m][n], 0, 0, 0); __builtin_amdgcn_s_setprio(0); } while (0)
; #define PG8_WAIT_V(n) asm volatile("s_waitcnt vmcnt(" #n ")" ::: "memory")
; #define PG8_WAIT_L(n) asm volatile("s_waitcnt lgkmcnt(" #n ")" ::: "memory")
; #define PG8_BAR __builtin_amdgcn_s_barrier()
; #define PG8_SCHED __builtin_amdgcn_sched_barrier(0)
;     __device__ __forceinline__ void operator()(const f32x4 (&acc)[2][2][4][2], const Unit& u, int wr, int wc, int fr, int fq) const {
;         const int row0 = u.pm * BM + wr * 64 + fr, col0 = u.pn * HALF + wc * 32 + 8 * fq;
; #pragma unroll
;         for (int ai = 0; ai < 2; ++ai)
; #pragma unroll
;             for (int m = 0; m < 4; ++m) {
;                 bf16_t* p = O + (size_t)(row0 + ai * HALF + m * 16) * ldc + col0;
;                 const f32x4 g0 = acc[ai][0][m][0], g1 = acc[ai][0][m][1], u0 = acc[ai][1][m][0], u1 = acc[ai][1][m][1];
;                 u32x4 w;
;                 w.x = cvtpk(silu_mul(g0[0], u0[0]), silu_mul(g0[1], u0[1])); w.y = cvtpk(silu_mul(g0[2], u0[2]), silu_mul(g0[3], u0[3]));
;                 w.z = cvtpk(silu_mul(g1[0], u1[0]), silu_mul(g1[1], u1[1])); w.w = cvtpk(silu_mul(g1[2], u1[2]), silu_mul(g1[3], u1[3]));
;                 __builtin_nontemporal_store(w, (PG8_GAS u32x4*)p);
; template <class Epi, class Sched, bool ALIGN_EPI = false, bool SP2 = false>
; __device__ __forceinline__ void gemm_phase(PG8_LAS unsigned char* lds, const Gemm g, const Sched& S, const Epi& E, const int tid) {
;     ...
;             PG8_WAIT_V(8); PG8_WAIT_L(0); PG8_BAR; PG8_MMA(1, 0, At, B0); PG8_MMA(1, 1, At, B1); PG8_BAR; PG8_SCHED;
	s_waitcnt lgkmcnt(0)
	v_mfma_f32_16x16x32_bf16 v[62:65], v[142:145], v[178:181], v[62:65]
	v_mfma_f32_16x16x32_bf16 v[54:57], v[154:157], v[178:181], v[54:57]
	v_mfma_f32_16x16x32_bf16 v[46:49], v[142:145], v[186:189], v[46:49]
	v_mfma_f32_16x16x32_bf16 v[38:41], v[154:157], v[186:189], v[38:41]
	v_mfma_f32_16x16x32_bf16 v[30:33], v[142:145], v[208:211], v[30:33]
	v_mfma_f32_16x16x32_bf16 v[22:25], v[154:157], v[208:211], v[22:25]
	v_mfma_f32_16x16x32_bf16 v[14:17], v[142:145], v[230:233], v[14:17]
	v_mfma_f32_16x16x32_bf16 v[10:13], v[154:157], v[230:233], v[10:13]
	v_mfma_f32_16x16x32_bf16 v[62:65], v[150:153], v[182:185], v[62:65]
	v_mfma_f32_16x16x32_bf16 v[54:57], v[158:161], v[182:185], v[54:57]
	v_mfma_f32_16x16x32_bf16 v[46:49], v[150:153], v[190:193], v[46:49]
	v_mfma_f32_16x16x32_bf16 v[38:41], v[158:161], v[190:193], v[38:41]
	v_mfma_f32_16x16x32_bf16 v[30:33], v[150:153], v[226:229], v[30:33]
	v_mfma_f32_16x16x32_bf16 v[22:25], v[158:161], v[226:229], v[22:25]
	v_mfma_f32_16x16x32_bf16 v[14:17], v[150:153], v[234:237], v[14:17]
	v_mfma_f32_16x16x32_bf16 v[10:13], v[158:161], v[234:237], v[10:13]
	v_mfma_f32_16x16x32_bf16 v[66:69], v[162:165], v[178:181], v[66:69]
	v_mfma_f32_16x16x32_bf16 v[58:61], v[170:173], v[178:181], v[58:61]
	v_mfma_f32_16x16x32_bf16 v[50:53], v[162:165], v[186:189], v[50:53]
	v_mfma_f32_16x16x32_bf16 v[42:45], v[170:173], v[186:189], v[42:45]
	v_mfma_f32_16x16x32_bf16 v[34:37], v[162:165], v[208:211], v[34:37]
	v_mfma_f32_16x16x32_bf16 v[26:29], v[170:173], v[208:211], v[26:29]
	v_mfma_f32_16x16x32_bf16 v[18:21], v[162:165], v[230:233], v[18:21]
	v_mfma_f32_16x16x32_bf16 v[6:9], v[170:173], v[230:233], v[6:9]
	v_mfma_f32_16x16x32_bf16 v[66:69], v[166:169], v[182:185], v[66:69]
	v_mfma_f32_16x16x32_bf16 v[58:61], v[174:177], v[182:185], v[58:61]
	v_mfma_f32_16x16x32_bf16 v[50:53], v[166:169], v[190:193], v[50:53]
	v_mfma_f32_16x16x32_bf16 v[42:45], v[174:177], v[190:193], v[42:45]
	v_mfma_f32_16x16x32_bf16 v[34:37], v[166:169], v[226:229], v[34:37]
	v_mfma_f32_16x16x32_bf16 v[26:29], v[174:177], v[226:229], v[26:29]
	v_mfma_f32_16x16x32_bf16 v[18:21], v[166:169], v[234:237], v[18:21]
	v_mfma_f32_16x16x32_bf16 v[6:9], v[174:177], v[234:237], v[6:9]
	s_barrier
	s_add_i32 s43, s43, 2
	s_add_u32 s40, s40, 0x100
	s_addc_u32 s42, s42, 0
	s_add_u32 s82, s82, 0x100
	s_addc_u32 s83, s83, 0
	s_cmp_gt_u32 s43, 13
	s_cbranch_scc0 .LBB0_188
.LBB0_191:
	s_setprio 0
	s_mov_b32 s54, 0xbfb8aa3b
	s_mov_b32 s55, 0xbfb8aa3b
	v_lshl_add_u32 v149, s33, 8, v5
	v_lshl_or_b32 v144, s31, 7, v147
	v_ashrrev_i32_e32 v145, 31, v144
	v_mov_b64_e32 v[142:143], s[6:7]
	v_mad_i64_i32 v[150:151], s[36:37], v149, s93, v[142:143]
	v_lshlrev_b64 v[144:145], 1, v[144:145]
	v_mov_b32_e32 v156, 0x16000
	v_mov_b32_e32 v158, 0x6e000
	v_mov_b32_e32 v157, 0
	v_mov_b32_e32 v159, 0
	v_lshl_add_u64 v[150:151], v[150:151], 0, v[144:145]
	v_pk_mul_f32 v[152:153], v[126:127], s[54:55]
	v_pk_mul_f32 v[154:155], v[128:129], s[54:55]
	v_exp_f32_e32 v152, v152
	v_exp_f32_e32 v153, v153
	v_exp_f32_e32 v154, v154
	v_exp_f32_e32 v155, v155
	v_pk_mul_f32 v[126:127], v[126:127], v[130:131]
	v_pk_mul_f32 v[128:129], v[128:129], v[132:133]
	v_pk_add_f32 v[152:153], v[152:153], 1.0 op_sel_hi:[1,0]
	v_pk_add_f32 v[154:155], v[154:155], 1.0 op_sel_hi:[1,0]
	v_rcp_f32_e32 v152, v152
	v_rcp_f32_e32 v153, v153
	v_rcp_f32_e32 v154, v154
	v_rcp_f32_e32 v155, v155
	v_pk_mul_f32 v[126:127], v[152:153], v[126:127]
	v_pk_mul_f32 v[128:129], v[154:155], v[128:129]
	v_cvt_pk_bf16_f32 v126, v126, v127
	v_cvt_pk_bf16_f32 v127, v128, v129
	v_pk_mul_f32 v[152:153], v[118:119], s[54:55]
	v_pk_mul_f32 v[154:155], v[120:121], s[54:55]
	v_exp_f32_e32 v152, v152
	v_exp_f32_e32 v153, v153
	v_exp_f32_e32 v154, v154
	v_exp_f32_e32 v155, v155
	v_pk_mul_f32 v[118:119], v[118:119], v[122:123]
	v_pk_mul_f32 v[120:121], v[120:121], v[124:125]
	v_pk_add_f32 v[152:153], v[152:153], 1.0 op_sel_hi:[1,0]
	v_pk_add_f32 v[154:155], v[154:155], 1.0 op_sel_hi:[1,0]
	v_rcp_f32_e32 v152, v152
	v_rcp_f32_e32 v153, v153
	v_rcp_f32_e32 v154, v154
	v_rcp_f32_e32 v155, v155
	v_pk_mul_f32 v[118:119], v[152:153], v[118:119]
	v_pk_mul_f32 v[120:121], v[154:155], v[120:121]
	v_cvt_pk_bf16_f32 v128, v118, v119
	v_cvt_pk_bf16_f32 v129, v120, v121
	global_store_dwordx4 v[150:151], v[126:129], off nt
	v_lshl_add_u64 v[150:151], v[150:151], 0, v[156:157]
	s_cmp_eq_u64 s[72:73], 0
	s_cbranch_scc1 .Lup_epi_nobar
	s_barrier

; #define PG8_STAGE(bufoff, gbase, voff) do { _Pragma("unroll") for (int _i = 0; _i < 2; ++_i) \
;         __builtin_amdgcn_global_load_lds((const unsigned*)((const char*)(gbase) + (voff)[_i]), (PG8_LAS unsigned*)(lds + (bufoff) + ldsw + _i * 8192), 16, 0, 0); } while (0)
; #define PG8_LDA(dst, b, h) do { _Pragma("unroll") for (int m = 0; m < 4; ++m) _Pragma("unroll") for (int k = 0; k < 2; ++k) dst[m][k] = *(const PG8_LAS bf16x8*)(lds + PG8_SA(b, h) + aoff + m * 2048 + k * 1024); } while (0)
; #define PG8_LDB(dst, b, h) do { _Pragma("unroll") for (int n = 0; n < 2; ++n) _Pragma("unroll") for (int k = 0; k < 2; ++k) dst[n][k] = *(const PG8_LAS bf16x8*)(lds + PG8_SB(b, h) + boff + n * 2048 + k * 1024); } while (0)
; #define PG8_WAIT_V(n) asm volatile("s_waitcnt vmcnt(" #n ")" ::: "memory")
; #define PG8_WAIT_L(n) asm volatile("s_waitcnt lgkmcnt(" #n ")" ::: "memory")
; #define PG8_BAR __builtin_amdgcn_s_barrier()
; template <class Epi, class Sched, bool ALIGN_EPI = false, bool SP2 = false>
; __device__ __forceinline__ void gemm_phase(PG8_LAS unsigned char* lds, const Gemm g, const Sched& S, const Epi& E, const int tid) {
;     ...
;         const bool has_next = S.next(ui + 1, nxt);
;         const char* nA = has_next ? (const char*)g.A + (size_t)nxt.pm * tstep : cA; const char* nB = has_next ? (const char*)g.Bt + (size_t)nxt.pn * tstep : cB;
;         for (int t = 0; t < nt; t += 2) {
;             if constexpr (Epi::MIDK) { if (t == E.midk) E.mid(acc, cur, wr, fr); }
;             const bool last = (t == nt - 2);
;             const char* a1 = cA + (size_t)(t + 1) * kstep;
;             const char* a2 = last ? nA : cA + (size_t)(t + 2) * kstep; const char* b2 = last ? nB : cB + (size_t)(t + 2) * kstep;
;             const char* a3 = a2 + kstep; const char* b3 = b2 + kstep;
;             if (last && has_next) S.a_ready(nxt);
;             if constexpr (SP2) {
;             PG8_LDB(B0, 0, 0); PG8_LDB(B1, 0, 1); PG8_SCHED; PG8_LDA(At, 0, 0); PG8_STAGE(PG8_SA(1, 1), a1 + hstep, voffA);
;             PG8_WAIT_V(8); PG8_WAIT_L(0); PG8_BAR; PG8_MMA(0, 0, At, B0); PG8_MMA(0, 1, At, B1); PG8_BAR; PG8_SCHED;
;             PG8_LDA(At, 0, 1); PG8_STAGE(PG8_SB(0, 0), b2, voffB); PG8_STAGE(PG8_SB(0, 1), b2 + hstep, voffB); PG8_STAGE(PG8_SA(0, 0), a2, voffA);
;             PG8_WAIT_V(8); PG8_WAIT_L(0); PG8_BAR; PG8_MMA(1, 0, At, B0); PG8_MMA(1, 1, At, B1); PG8_BAR; PG8_SCHED;
.LBB0_253:
	s_ashr_i32 s81, s80, 31
	s_lshl_b64 s[24:25], s[80:81], 19
	s_add_u32 s84, s13, s24
	s_addc_u32 s85, s18, s25
	s_and_b64 s[24:25], s[4:5], exec
	s_cselect_b32 s17, s85, s7
	s_cselect_b32 s24, s84, s6
	s_ashr_i32 s83, s82, 31
	s_lshl_b64 s[42:43], s[82:83], 19
	s_add_u32 s86, s19, s42
	s_addc_u32 s87, s20, s43
	s_and_b64 s[42:43], s[4:5], exec
	s_cselect_b32 s25, s87, s89
	s_cselect_b32 s33, s86, s88
	s_add_u32 s40, s88, 0x100
	s_addc_u32 s42, s89, 0
	s_add_u32 s6, s6, 0x40080
	s_addc_u32 s7, s7, 0
	s_mov_b32 s43, -2
	s_waitcnt vmcnt(0)
	s_cmp_eq_u64 s[76:77], 0
	s_cbranch_scc1 .Lprio_proj
	s_setprio 1
.Lprio_proj:
	s_add_u32 s46, s6, 0xfffc0080
	s_addc_u32 s54, s7, -1
	s_add_i32 s55, 0, 0x10000
	s_cmp_eq_u32 s43, 12
	s_cselect_b32 s91, s17, s54
	s_cselect_b32 s90, s24, s46
	v_add_u32_e32 v0, s55, v164
	s_cselect_b32 s89, s25, s42
	s_cselect_b32 s88, s33, s40
	s_add_i32 s46, 0, 0x14000
	ds_read_b128 v[144:147], v0
	ds_read_b128 v[148:151], v0 offset:1024
	ds_read_b128 v[152:155], v0 offset:2048
	ds_read_b128 v[156:159], v0 offset:3072
	v_add_u32_e32 v0, s46, v164
	ds_read_b128 v[160:163], v0
	ds_read_b128 v[168:171], v0 offset:1024
	ds_read_b128 v[172:175], v0 offset:2048
	ds_read_b128 v[176:179], v0 offset:3072
	v_lshl_add_u64 v[238:239], s[6:7], 0, v[142:143]
	s_add_i32 m0, s30, 0xc000
	ds_read_b128 v[180:183], v166
	ds_read_b128 v[184:187], v166 offset:1024
	ds_read_b128 v[188:191], v166 offset:2048
	ds_read_b128 v[192:195], v166 offset:3072
	ds_read_b128 v[208:211], v166 offset:4096
	ds_read_b128 v[226:229], v166 offset:5120
	ds_read_b128 v[230:233], v166 offset:6144
	ds_read_b128 v[234:237], v166 offset:7168
	global_load_lds_dwordx4 v[238:239], off
	v_lshl_add_u64 v[238:239], s[6:7], 0, v[140:141]
	s_add_i32 m0, s30, 0xe000
	s_nop 0
	global_load_lds_dwordx4 v[238:239], off
	s_waitcnt vmcnt(8)
	s_waitcnt lgkmcnt(0)
	s_barrier
	s_waitcnt lgkmcnt(0)
	v_mfma_f32_16x16x32_bf16 v[130:133], v[144:147], v[180:183], 0
	v_mfma_f32_16x16x32_bf16 v[126:129], v[152:155], v[180:183], 0
	v_mfma_f32_16x16x32_bf16 v[114:117], v[144:147], v[188:191], 0
	v_mfma_f32_16x16x32_bf16 v[110:113], v[152:155], v[188:191], 0
	v_mfma_f32_16x16x32_bf16 v[98:101], v[144:147], v[208:211], 0
	v_mfma_f32_16x16x32_bf16 v[94:97], v[152:155], v[208:211], 0
	v_mfma_f32_16x16x32_bf16 v[82:85], v[144:147], v[230:233], 0
	v_mfma_f32_16x16x32_bf16 v[78:81], v[152:155], v[230:233], 0
	v_mfma_f32_16x16x32_bf16 v[130:133], v[148:151], v[184:187], v[130:133]
	v_mfma_f32_16x16x32_bf16 v[126:129], v[156:159], v[184:187], v[126:129]
	v_mfma_f32_16x16x32_bf16 v[114:117], v[148:151], v[192:195], v[114:117]
	v_mfma_f32_16x16x32_bf16 v[110:113], v[156:159], v[192:195], v[110:113]
	v_mfma_f32_16x16x32_bf16 v[98:101], v[148:151], v[226:229], v[98:101]
	v_mfma_f32_16x16x32_bf16 v[94:97], v[156:159], v[226:229], v[94:97]
	v_mfma_f32_16x16x32_bf16 v[82:85], v[148:151], v[234:237], v[82:85]
	v_mfma_f32_16x16x32_bf16 v[78:81], v[156:159], v[234:237], v[78:81]
	v_mfma_f32_16x16x32_bf16 v[122:125], v[160:163], v[180:183], 0
	v_mfma_f32_16x16x32_bf16 v[118:121], v[172:175], v[180:183], 0
	v_mfma_f32_16x16x32_bf16 v[106:109], v[160:163], v[188:191], 0
	v_mfma_f32_16x16x32_bf16 v[102:105], v[172:175], v[188:191], 0
	v_mfma_f32_16x16x32_bf16 v[90:93], v[160:163], v[208:211], 0
	v_mfma_f32_16x16x32_bf16 v[86:89], v[172:175], v[208:211], 0
	v_mfma_f32_16x16x32_bf16 v[74:77], v[160:163], v[230:233], 0
	v_mfma_f32_16x16x32_bf16 v[70:73], v[172:175], v[230:233], 0
	v_mfma_f32_16x16x32_bf16 v[122:125], v[168:171], v[184:187], v[122:125]
	v_mfma_f32_16x16x32_bf16 v[118:121], v[176:179], v[184:187], v[118:121]
	v_mfma_f32_16x16x32_bf16 v[106:109], v[168:171], v[192:195], v[106:109]
	v_mfma_f32_16x16x32_bf16 v[102:105], v[176:179], v[192:195], v[102:105]
	v_mfma_f32_16x16x32_bf16 v[90:93], v[168:171], v[226:229], v[90:93]
	v_mfma_f32_16x16x32_bf16 v[86:89], v[176:179], v[226:229], v[86:89]
	v_mfma_f32_16x16x32_bf16 v[74:77], v[168:171], v[234:237], v[74:77]
	v_mfma_f32_16x16x32_bf16 v[70:73], v[176:179], v[234:237], v[70:73]
	s_barrier
	s_add_i32 s54, s55, s28
	v_lshl_add_u64 v[238:239], s[88:89], 0, v[136:137]
	s_mov_b32 m0, s54
	ds_read_b128 v[180:183], v166 offset:16384
	ds_read_b128 v[184:187], v166 offset:17408
	ds_read_b128 v[188:191], v166 offset:18432
	ds_read_b128 v[192:195], v166 offset:19456
	ds_read_b128 v[208:211], v166 offset:20480
	ds_read_b128 v[226:229], v166 offset:21504
	ds_read_b128 v[230:233], v166 offset:22528
	ds_read_b128 v[234:237], v166 offset:23552
	global_load_lds_dwordx4 v[238:239], off
	s_add_i32 m0, s54, 0x2000
	s_add_u32 s54, s88, 0x40000
	v_lshl_add_u64 v[240:241], s[88:89], 0, v[2:3]
	s_addc_u32 s55, s89, 0
	s_add_i32 s46, s46, s28
	global_load_lds_dwordx4 v[240:241], off
	v_lshl_add_u64 v[242:243], s[54:55], 0, v[136:137]
	s_mov_b32 m0, s46
	v_lshl_add_u64 v[244:245], s[90:91], 0, v[134:135]
	global_load_lds_dwordx4 v[242:243], off
	v_lshl_add_u64 v[242:243], s[54:55], 0, v[2:3]
	s_add_i32 m0, s46, 0x2000
	s_nop 0
	global_load_lds_dwordx4 v[242:243], off
	v_lshl_add_u64 v[242:243], s[90:91], 0, v[138:139]
	s_mov_b32 m0, s30
	s_nop 0
	global_load_lds_dwordx4 v[242:243], off
	s_mov_b32 m0, s31
	s_nop 0
	global_load_lds_dwordx4 v[244:245], off
	s_waitcnt vmcnt(8)
	s_waitcnt lgkmcnt(0)
	s_barrier
; #define PG8_STAGE(bufoff, gbase, voff) do { _Pragma("unroll") for (int _i = 0; _i < 2; ++_i) \
;         __builtin_amdgcn_global_load_lds((const unsigned*)((const char*)(gbase) + (voff)[_i]), (PG8_LAS unsigned*)(lds + (bufoff) + ldsw + _i * 8192), 16, 0, 0); } while (0)
; #define PG8_LDA(dst, b, h) do { _Pragma("unroll") for (int m = 0; m < 4; ++m) _Pragma("unroll") for (int k = 0; k < 2; ++k) dst[m][k] = *(const PG8_LAS bf16x8*)(lds + PG8_SA(b, h) + aoff + m * 2048 + k * 1024); } while (0)
; #define PG8_LDB(dst, b, h) do { _Pragma("unroll") for (int n = 0; n < 2; ++n) _Pragma("unroll") for (int k = 0; k < 2; ++k) dst[n][k] = *(const PG8_LAS bf16x8*)(lds + PG8_SB(b, h) + boff + n * 2048 + k * 1024); } while (0)
; #define PG8_MMA(ai, bj, At, Bt) do { __builtin_amdgcn_s_setprio(1); _Pragma("unroll") for (int m = 0; m < 4; ++m) _Pragma("unroll") for (int n = 0; n < 2; ++n) _Pragma("unroll") for (int k = 0; k < 2; ++k) \
;         acc[ai][bj][m][n] = __builtin_amdgcn_mfma_f32_16x16x32_bf16(Bt[n][k], At[m][k], acc[ai][bj][m][n], 0, 0, 0); __builtin_amdgcn_s_setprio(0); } while (0)
; #define PG8_WAIT_V(n) asm volatile("s_waitcnt vmcnt(" #n ")" ::: "memory")
; #define PG8_WAIT_L(n) asm volatile("s_waitcnt lgkmcnt(" #n ")" ::: "memory")
; #define PG8_BAR __builtin_amdgcn_s_barrier()
; #define PG8_SCHED __builtin_amdgcn_sched_barrier(0)
; template <class Epi, class Sched, bool ALIGN_EPI = false, bool SP2 = false>
; __device__ __forceinline__ void gemm_phase(PG8_LAS unsigned char* lds, const Gemm g, const Sched& S, const Epi& E, const int tid) {
;     ...
;             PG8_WAIT_V(8); PG8_WAIT_L(0); PG8_BAR; PG8_MMA(1, 0, At, B0); PG8_MMA(1, 1, At, B1); PG8_BAR; PG8_SCHED;
;             PG8_LDB(B0, 1, 0); PG8_LDB(B1, 1, 1); PG8_SCHED; PG8_LDA(At, 1, 0); PG8_STAGE(PG8_SA(0, 1), a2 + hstep, voffA);
;             PG8_WAIT_V(8); PG8_WAIT_L(0); PG8_BAR; PG8_MMA(0, 0, At, B0); PG8_MMA(0, 1, At, B1); PG8_BAR; PG8_SCHED;
	s_waitcnt lgkmcnt(0)
	v_mfma_f32_16x16x32_bf16 v[66:69], v[144:147], v[180:183], 0
	v_mfma_f32_16x16x32_bf16 v[62:65], v[152:155], v[180:183], 0
	v_mfma_f32_16x16x32_bf16 v[50:53], v[144:147], v[188:191], 0
	v_mfma_f32_16x16x32_bf16 v[46:49], v[152:155], v[188:191], 0
	v_mfma_f32_16x16x32_bf16 v[34:37], v[144:147], v[208:211], 0
	v_mfma_f32_16x16x32_bf16 v[30:33], v[152:155], v[208:211], 0
	v_mfma_f32_16x16x32_bf16 v[18:21], v[144:147], v[230:233], 0
	v_mfma_f32_16x16x32_bf16 v[14:17], v[152:155], v[230:233], 0
	v_mfma_f32_16x16x32_bf16 v[66:69], v[148:151], v[184:187], v[66:69]
	v_mfma_f32_16x16x32_bf16 v[62:65], v[156:159], v[184:187], v[62:65]
	v_mfma_f32_16x16x32_bf16 v[50:53], v[148:151], v[192:195], v[50:53]
	v_mfma_f32_16x16x32_bf16 v[46:49], v[156:159], v[192:195], v[46:49]
	v_mfma_f32_16x16x32_bf16 v[34:37], v[148:151], v[226:229], v[34:37]
	v_mfma_f32_16x16x32_bf16 v[30:33], v[156:159], v[226:229], v[30:33]
	v_mfma_f32_16x16x32_bf16 v[18:21], v[148:151], v[234:237], v[18:21]
	v_mfma_f32_16x16x32_bf16 v[14:17], v[156:159], v[234:237], v[14:17]
	v_mfma_f32_16x16x32_bf16 v[58:61], v[160:163], v[180:183], 0
	v_mfma_f32_16x16x32_bf16 v[54:57], v[172:175], v[180:183], 0
	v_mfma_f32_16x16x32_bf16 v[42:45], v[160:163], v[188:191], 0
	v_mfma_f32_16x16x32_bf16 v[38:41], v[172:175], v[188:191], 0
	v_mfma_f32_16x16x32_bf16 v[26:29], v[160:163], v[208:211], 0
	v_mfma_f32_16x16x32_bf16 v[22:25], v[172:175], v[208:211], 0
	v_mfma_f32_16x16x32_bf16 v[10:13], v[160:163], v[230:233], 0
	v_mfma_f32_16x16x32_bf16 v[6:9], v[172:175], v[230:233], 0
	v_mfma_f32_16x16x32_bf16 v[58:61], v[168:171], v[184:187], v[58:61]
	v_mfma_f32_16x16x32_bf16 v[54:57], v[176:179], v[184:187], v[54:57]
	v_mfma_f32_16x16x32_bf16 v[42:45], v[168:171], v[192:195], v[42:45]
	v_mfma_f32_16x16x32_bf16 v[38:41], v[176:179], v[192:195], v[38:41]
	v_mfma_f32_16x16x32_bf16 v[26:29], v[168:171], v[226:229], v[26:29]
	v_mfma_f32_16x16x32_bf16 v[22:25], v[176:179], v[226:229], v[22:25]
	v_mfma_f32_16x16x32_bf16 v[10:13], v[168:171], v[234:237], v[10:13]
	v_mfma_f32_16x16x32_bf16 v[6:9], v[176:179], v[234:237], v[6:9]
	s_barrier
	s_add_i32 s46, 0, 0x18000
	v_add_u32_e32 v0, s46, v164
	s_add_i32 s81, 0, 0x1c000
	ds_read_b128 v[144:147], v0
	ds_read_b128 v[148:151], v0 offset:1024
	ds_read_b128 v[152:155], v0 offset:2048
	ds_read_b128 v[156:159], v0 offset:3072
	v_add_u32_e32 v0, s81, v164
	ds_read_b128 v[160:163], v0
	ds_read_b128 v[168:171], v0 offset:1024
	ds_read_b128 v[172:175], v0 offset:2048
	ds_read_b128 v[176:179], v0 offset:3072
	s_add_u32 s54, s90, 0x40000
	s_addc_u32 s55, s91, 0
	s_mov_b32 m0, s34
	v_lshl_add_u64 v[246:247], s[54:55], 0, v[138:139]
	ds_read_b128 v[180:183], v166 offset:32768
	ds_read_b128 v[184:187], v166 offset:33792
	ds_read_b128 v[188:191], v166 offset:34816
	ds_read_b128 v[192:195], v166 offset:35840
	ds_read_b128 v[208:211], v166 offset:36864
	ds_read_b128 v[226:229], v166 offset:37888
	ds_read_b128 v[230:233], v166 offset:38912
	ds_read_b128 v[234:237], v166 offset:39936
	global_load_lds_dwordx4 v[246:247], off
	v_lshl_add_u64 v[246:247], s[54:55], 0, v[134:135]
	s_mov_b32 m0, s36
	s_nop 0
	global_load_lds_dwordx4 v[246:247], off
	s_waitcnt vmcnt(8)
	s_waitcnt lgkmcnt(0)
	s_barrier
	s_waitcnt lgkmcnt(0)
	v_mfma_f32_16x16x32_bf16 v[130:133], v[144:147], v[180:183], v[130:133]
	v_mfma_f32_16x16x32_bf16 v[126:129], v[152:155], v[180:183], v[126:129]
	v_mfma_f32_16x16x32_bf16 v[114:117], v[144:147], v[188:191], v[114:117]
	v_mfma_f32_16x16x32_bf16 v[110:113], v[152:155], v[188:191], v[110:113]
	v_mfma_f32_16x16x32_bf16 v[98:101], v[144:147], v[208:211], v[98:101]
	v_mfma_f32_16x16x32_bf16 v[94:97], v[152:155], v[208:211], v[94:97]
	v_mfma_f32_16x16x32_bf16 v[82:85], v[144:147], v[230:233], v[82:85]
	v_mfma_f32_16x16x32_bf16 v[78:81], v[152:155], v[230:233], v[78:81]
	v_mfma_f32_16x16x32_bf16 v[130:133], v[148:151], v[184:187], v[130:133]
	v_mfma_f32_16x16x32_bf16 v[126:129], v[156:159], v[184:187], v[126:129]
	v_mfma_f32_16x16x32_bf16 v[114:117], v[148:151], v[192:195], v[114:117]
	v_mfma_f32_16x16x32_bf16 v[110:113], v[156:159], v[192:195], v[110:113]
	v_mfma_f32_16x16x32_bf16 v[98:101], v[148:151], v[226:229], v[98:101]
	v_mfma_f32_16x16x32_bf16 v[94:97], v[156:159], v[226:229], v[94:97]
	v_mfma_f32_16x16x32_bf16 v[82:85], v[148:151], v[234:237], v[82:85]
	v_mfma_f32_16x16x32_bf16 v[78:81], v[156:159], v[234:237], v[78:81]
	v_mfma_f32_16x16x32_bf16 v[122:125], v[160:163], v[180:183], v[122:125]
	v_mfma_f32_16x16x32_bf16 v[118:121], v[172:175], v[180:183], v[118:121]
	v_mfma_f32_16x16x32_bf16 v[106:109], v[160:163], v[188:191], v[106:109]
	v_mfma_f32_16x16x32_bf16 v[102:105], v[172:175], v[188:191], v[102:105]
	v_mfma_f32_16x16x32_bf16 v[90:93], v[160:163], v[208:211], v[90:93]
	v_mfma_f32_16x16x32_bf16 v[86:89], v[172:175], v[208:211], v[86:89]
	v_mfma_f32_16x16x32_bf16 v[74:77], v[160:163], v[230:233], v[74:77]
	v_mfma_f32_16x16x32_bf16 v[70:73], v[172:175], v[230:233], v[70:73]
	v_mfma_f32_16x16x32_bf16 v[122:125], v[168:171], v[184:187], v[122:125]
	v_mfma_f32_16x16x32_bf16 v[118:121], v[176:179], v[184:187], v[118:121]
	v_mfma_f32_16x16x32_bf16 v[106:109], v[168:171], v[192:195], v[106:109]
	v_mfma_f32_16x16x32_bf16 v[102:105], v[176:179], v[192:195], v[102:105]
	v_mfma_f32_16x16x32_bf16 v[90:93], v[168:171], v[226:229], v[90:93]
	v_mfma_f32_16x16x32_bf16 v[86:89], v[176:179], v[226:229], v[86:89]
	v_mfma_f32_16x16x32_bf16 v[74:77], v[168:171], v[234:237], v[74:77]
	v_mfma_f32_16x16x32_bf16 v[70:73], v[176:179], v[234:237], v[70:73]
	s_barrier
; #define PG8_STAGE(bufoff, gbase, voff) do { _Pragma("unroll") for (int _i = 0; _i < 2; ++_i) \
;         __builtin_amdgcn_global_load_lds((const unsigned*)((const char*)(gbase) + (voff)[_i]), (PG8_LAS unsigned*)(lds + (bufoff) + ldsw + _i * 8192), 16, 0, 0); } while (0)
; #define PG8_LDA(dst, b, h) do { _Pragma("unroll") for (int m = 0; m < 4; ++m) _Pragma("unroll") for (int k = 0; k < 2; ++k) dst[m][k] = *(const PG8_LAS bf16x8*)(lds + PG8_SA(b, h) + aoff + m * 2048 + k * 1024); } while (0)
; #define PG8_LDB(dst, b, h) do { _Pragma("unroll") for (int n = 0; n < 2; ++n) _Pragma("unroll") for (int k = 0; k < 2; ++k) dst[n][k] = *(const PG8_LAS bf16x8*)(lds + PG8_SB(b, h) + boff + n * 2048 + k * 1024); } while (0)
; #define PG8_MMA(ai, bj, At, Bt) do { __builtin_amdgcn_s_setprio(1); _Pragma("unroll") for (int m = 0; m < 4; ++m) _Pragma("unroll") for (int n = 0; n < 2; ++n) _Pragma("unroll") for (int k = 0; k < 2; ++k) \
;         acc[ai][bj][m][n] = __builtin_amdgcn_mfma_f32_16x16x32_bf16(Bt[n][k], At[m][k], acc[ai][bj][m][n], 0, 0, 0); __builtin_amdgcn_s_setprio(0); } while (0)
; #define PG8_WAIT_V(n) asm volatile("s_waitcnt vmcnt(" #n ")" ::: "memory")
; #define PG8_WAIT_L(n) asm volatile("s_waitcnt lgkmcnt(" #n ")" ::: "memory")
; #define PG8_BAR __builtin_amdgcn_s_barrier()
; #define PG8_SCHED __builtin_amdgcn_sched_barrier(0)
; template <class Epi, class Sched, bool ALIGN_EPI = false, bool SP2 = false>
; __device__ __forceinline__ void gemm_phase(PG8_LAS unsigned char* lds, const Gemm g, const Sched& S, const Epi& E, const int tid) {
;     ...
;             PG8_LDB(B0, 0, 0); PG8_LDB(B1, 0, 1); PG8_SCHED; PG8_LDA(At, 0, 0); PG8_STAGE(PG8_SA(1, 1), a1 + hstep, voffA);
;     ...
;             PG8_LDA(At, 1, 1); PG8_STAGE(PG8_SB(1, 0), b3, voffB); PG8_STAGE(PG8_SB(1, 1), b3 + hstep, voffB); PG8_STAGE(PG8_SA(1, 0), a3, voffA);
;             PG8_WAIT_V(8); PG8_WAIT_L(0); PG8_BAR; PG8_MMA(1, 0, At, B0); PG8_MMA(1, 1, At, B1); PG8_BAR; PG8_SCHED;
	s_add_i32 s46, s46, s28
	v_lshl_add_u64 v[238:239], v[238:239], 0, s[50:51]
	s_mov_b32 m0, s46
	ds_read_b128 v[180:183], v166 offset:49152
	ds_read_b128 v[184:187], v166 offset:50176
	ds_read_b128 v[188:191], v166 offset:51200
	ds_read_b128 v[192:195], v166 offset:52224
	ds_read_b128 v[208:211], v166 offset:53248
	ds_read_b128 v[226:229], v166 offset:54272
	ds_read_b128 v[230:233], v166 offset:55296
	ds_read_b128 v[234:237], v166 offset:56320
	global_load_lds_dwordx4 v[238:239], off
	s_add_i32 m0, s46, 0x2000
	s_add_u32 s54, s88, 0x40080
	v_lshl_add_u64 v[238:239], v[240:241], 0, s[50:51]
	s_addc_u32 s55, s89, 0
	s_add_i32 s46, s81, s28
	global_load_lds_dwordx4 v[238:239], off
	v_lshl_add_u64 v[238:239], s[54:55], 0, v[136:137]
	s_mov_b32 m0, s46
	s_nop 0
	global_load_lds_dwordx4 v[238:239], off
	v_lshl_add_u64 v[238:239], s[54:55], 0, v[2:3]
	s_add_i32 m0, s46, 0x2000
	s_nop 0
	global_load_lds_dwordx4 v[238:239], off
	v_lshl_add_u64 v[238:239], v[242:243], 0, s[50:51]
	s_mov_b32 m0, s37
	s_nop 0
	global_load_lds_dwordx4 v[238:239], off
	v_lshl_add_u64 v[238:239], v[244:245], 0, s[50:51]
	s_mov_b32 m0, s38
	s_nop 0
	global_load_lds_dwordx4 v[238:239], off
	s_waitcnt vmcnt(8)
	s_waitcnt lgkmcnt(0)
	s_barrier
	s_waitcnt lgkmcnt(0)
	v_mfma_f32_16x16x32_bf16 v[66:69], v[144:147], v[180:183], v[66:69]
	v_mfma_f32_16x16x32_bf16 v[62:65], v[152:155], v[180:183], v[62:65]
	v_mfma_f32_16x16x32_bf16 v[50:53], v[144:147], v[188:191], v[50:53]
	v_mfma_f32_16x16x32_bf16 v[46:49], v[152:155], v[188:191], v[46:49]
	v_mfma_f32_16x16x32_bf16 v[34:37], v[144:147], v[208:211], v[34:37]
	v_mfma_f32_16x16x32_bf16 v[30:33], v[152:155], v[208:211], v[30:33]
	v_mfma_f32_16x16x32_bf16 v[18:21], v[144:147], v[230:233], v[18:21]
	v_mfma_f32_16x16x32_bf16 v[14:17], v[152:155], v[230:233], v[14:17]
	v_mfma_f32_16x16x32_bf16 v[66:69], v[148:151], v[184:187], v[66:69]
	v_mfma_f32_16x16x32_bf16 v[62:65], v[156:159], v[184:187], v[62:65]
	v_mfma_f32_16x16x32_bf16 v[50:53], v[148:151], v[192:195], v[50:53]
	v_mfma_f32_16x16x32_bf16 v[46:49], v[156:159], v[192:195], v[46:49]
	v_mfma_f32_16x16x32_bf16 v[34:37], v[148:151], v[226:229], v[34:37]
	v_mfma_f32_16x16x32_bf16 v[30:33], v[156:159], v[226:229], v[30:33]
	v_mfma_f32_16x16x32_bf16 v[18:21], v[148:151], v[234:237], v[18:21]
	v_mfma_f32_16x16x32_bf16 v[14:17], v[156:159], v[234:237], v[14:17]
	v_mfma_f32_16x16x32_bf16 v[58:61], v[160:163], v[180:183], v[58:61]
	v_mfma_f32_16x16x32_bf16 v[54:57], v[172:175], v[180:183], v[54:57]
	v_mfma_f32_16x16x32_bf16 v[42:45], v[160:163], v[188:191], v[42:45]
	v_mfma_f32_16x16x32_bf16 v[38:41], v[172:175], v[188:191], v[38:41]
	v_mfma_f32_16x16x32_bf16 v[26:29], v[160:163], v[208:211], v[26:29]
	v_mfma_f32_16x16x32_bf16 v[22:25], v[172:175], v[208:211], v[22:25]
	v_mfma_f32_16x16x32_bf16 v[10:13], v[160:163], v[230:233], v[10:13]
	v_mfma_f32_16x16x32_bf16 v[6:9], v[172:175], v[230:233], v[6:9]
	v_mfma_f32_16x16x32_bf16 v[58:61], v[168:171], v[184:187], v[58:61]
	v_mfma_f32_16x16x32_bf16 v[54:57], v[176:179], v[184:187], v[54:57]
	v_mfma_f32_16x16x32_bf16 v[42:45], v[168:171], v[192:195], v[42:45]
	v_mfma_f32_16x16x32_bf16 v[38:41], v[176:179], v[192:195], v[38:41]
	v_mfma_f32_16x16x32_bf16 v[26:29], v[168:171], v[226:229], v[26:29]
	v_mfma_f32_16x16x32_bf16 v[22:25], v[176:179], v[226:229], v[22:25]
	v_mfma_f32_16x16x32_bf16 v[10:13], v[168:171], v[234:237], v[10:13]
	v_mfma_f32_16x16x32_bf16 v[6:9], v[176:179], v[234:237], v[6:9]
	s_barrier
	s_add_i32 s43, s43, 2
	s_add_u32 s40, s40, 0x100
	s_addc_u32 s42, s42, 0
	s_add_u32 s6, s6, 0x100
	s_addc_u32 s7, s7, 0
	s_cmp_gt_u32 s43, 13
.LBB0_254:
	s_add_u32 s46, s6, 0xfffc0080
	s_addc_u32 s54, s7, -1
	s_add_i32 s55, 0, 0x10000
	s_cmp_eq_u32 s43, 12
	s_cselect_b32 s91, s17, s54
	s_cselect_b32 s90, s24, s46
	v_add_u32_e32 v0, s55, v164
	s_cselect_b32 s89, s25, s42
	s_cselect_b32 s88, s33, s40
	s_add_i32 s46, 0, 0x14000
	ds_read_b128 v[144:147], v0
	ds_read_b128 v[148:151], v0 offset:1024
	ds_read_b128 v[152:155], v0 offset:2048
	ds_read_b128 v[156:159], v0 offset:3072
	v_add_u32_e32 v0, s46, v164
	ds_read_b128 v[160:163], v0
	ds_read_b128 v[168:171], v0 offset:1024
	ds_read_b128 v[172:175], v0 offset:2048
	ds_read_b128 v[176:179], v0 offset:3072
	v_lshl_add_u64 v[238:239], s[6:7], 0, v[142:143]
	s_add_i32 m0, s30, 0xc000
	ds_read_b128 v[180:183], v166
	ds_read_b128 v[184:187], v166 offset:1024
	ds_read_b128 v[188:191], v166 offset:2048
	ds_read_b128 v[192:195], v166 offset:3072
	ds_read_b128 v[208:211], v166 offset:4096
	ds_read_b128 v[226:229], v166 offset:5120
	ds_read_b128 v[230:233], v166 offset:6144
	ds_read_b128 v[234:237], v166 offset:7168
	global_load_lds_dwordx4 v[238:239], off
	v_lshl_add_u64 v[238:239], s[6:7], 0, v[140:141]
	s_add_i32 m0, s30, 0xe000
	s_nop 0
	global_load_lds_dwordx4 v[238:239], off
	s_waitcnt vmcnt(8)
	s_waitcnt lgkmcnt(0)
	s_barrier
; #define PG8_STAGE(bufoff, gbase, voff) do { _Pragma("unroll") for (int _i = 0; _i < 2; ++_i) \
;         __builtin_amdgcn_global_load_lds((const unsigned*)((const char*)(gbase) + (voff)[_i]), (PG8_LAS unsigned*)(lds + (bufoff) + ldsw + _i * 8192), 16, 0, 0); } while (0)
; #define PG8_LDA(dst, b, h) do { _Pragma("unroll") for (int m = 0; m < 4; ++m) _Pragma("unroll") for (int k = 0; k < 2; ++k) dst[m][k] = *(const PG8_LAS bf16x8*)(lds + PG8_SA(b, h) + aoff + m * 2048 + k * 1024); } while (0)
; #define PG8_MMA(ai, bj, At, Bt) do { __builtin_amdgcn_s_setprio(1); _Pragma("unroll") for (int m = 0; m < 4; ++m) _Pragma("unroll") for (int n = 0; n < 2; ++n) _Pragma("unroll") for (int k = 0; k < 2; ++k) \
;         acc[ai][bj][m][n] = __builtin_amdgcn_mfma_f32_16x16x32_bf16(Bt[n][k], At[m][k], acc[ai][bj][m][n], 0, 0, 0); __builtin_amdgcn_s_setprio(0); } while (0)
; #define PG8_WAIT_V(n) asm volatile("s_waitcnt vmcnt(" #n ")" ::: "memory")
; #define PG8_WAIT_L(n) asm volatile("s_waitcnt lgkmcnt(" #n ")" ::: "memory")
; #define PG8_BAR __builtin_amdgcn_s_barrier()
; #define PG8_SCHED __builtin_amdgcn_sched_barrier(0)
; template <class Epi, class Sched, bool ALIGN_EPI = false, bool SP2 = false>
; __device__ __forceinline__ void gemm_phase(PG8_LAS unsigned char* lds, const Gemm g, const Sched& S, const Epi& E, const int tid) {
;     ...
;             PG8_WAIT_V(8); PG8_WAIT_L(0); PG8_BAR; PG8_MMA(0, 0, At, B0); PG8_MMA(0, 1, At, B1); PG8_BAR; PG8_SCHED;
;             PG8_LDA(At, 0, 1); PG8_STAGE(PG8_SB(0, 0), b2, voffB); PG8_STAGE(PG8_SB(0, 1), b2 + hstep, voffB); PG8_STAGE(PG8_SA(0, 0), a2, voffA);
;             PG8_WAIT_V(8); PG8_WAIT_L(0); PG8_BAR; PG8_MMA(1, 0, At, B0); PG8_MMA(1, 1, At, B1); PG8_BAR; PG8_SCHED;
	s_waitcnt lgkmcnt(0)
	v_mfma_f32_16x16x32_bf16 v[130:133], v[144:147], v[180:183], v[130:133]
	v_mfma_f32_16x16x32_bf16 v[126:129], v[152:155], v[180:183], v[126:129]
	v_mfma_f32_16x16x32_bf16 v[114:117], v[144:147], v[188:191], v[114:117]
	v_mfma_f32_16x16x32_bf16 v[110:113], v[152:155], v[188:191], v[110:113]
	v_mfma_f32_16x16x32_bf16 v[98:101], v[144:147], v[208:211], v[98:101]
	v_mfma_f32_16x16x32_bf16 v[94:97], v[152:155], v[208:211], v[94:97]
	v_mfma_f32_16x16x32_bf16 v[82:85], v[144:147], v[230:233], v[82:85]
	v_mfma_f32_16x16x32_bf16 v[78:81], v[152:155], v[230:233], v[78:81]
	v_mfma_f32_16x16x32_bf16 v[130:133], v[148:151], v[184:187], v[130:133]
	v_mfma_f32_16x16x32_bf16 v[126:129], v[156:159], v[184:187], v[126:129]
	v_mfma_f32_16x16x32_bf16 v[114:117], v[148:151], v[192:195], v[114:117]
	v_mfma_f32_16x16x32_bf16 v[110:113], v[156:159], v[192:195], v[110:113]
	v_mfma_f32_16x16x32_bf16 v[98:101], v[148:151], v[226:229], v[98:101]
	v_mfma_f32_16x16x32_bf16 v[94:97], v[156:159], v[226:229], v[94:97]
	v_mfma_f32_16x16x32_bf16 v[82:85], v[148:151], v[234:237], v[82:85]
	v_mfma_f32_16x16x32_bf16 v[78:81], v[156:159], v[234:237], v[78:81]
	v_mfma_f32_16x16x32_bf16 v[122:125], v[160:163], v[180:183], v[122:125]
	v_mfma_f32_16x16x32_bf16 v[118:121], v[172:175], v[180:183], v[118:121]
	v_mfma_f32_16x16x32_bf16 v[106:109], v[160:163], v[188:191], v[106:109]
	v_mfma_f32_16x16x32_bf16 v[102:105], v[172:175], v[188:191], v[102:105]
	v_mfma_f32_16x16x32_bf16 v[90:93], v[160:163], v[208:211], v[90:93]
	v_mfma_f32_16x16x32_bf16 v[86:89], v[172:175], v[208:211], v[86:89]
	v_mfma_f32_16x16x32_bf16 v[74:77], v[160:163], v[230:233], v[74:77]
	v_mfma_f32_16x16x32_bf16 v[70:73], v[172:175], v[230:233], v[70:73]
	v_mfma_f32_16x16x32_bf16 v[122:125], v[168:171], v[184:187], v[122:125]
	v_mfma_f32_16x16x32_bf16 v[118:121], v[176:179], v[184:187], v[118:121]
	v_mfma_f32_16x16x32_bf16 v[106:109], v[168:171], v[192:195], v[106:109]
	v_mfma_f32_16x16x32_bf16 v[102:105], v[176:179], v[192:195], v[102:105]
	v_mfma_f32_16x16x32_bf16 v[90:93], v[168:171], v[226:229], v[90:93]
	v_mfma_f32_16x16x32_bf16 v[86:89], v[176:179], v[226:229], v[86:89]
	v_mfma_f32_16x16x32_bf16 v[74:77], v[168:171], v[234:237], v[74:77]
	v_mfma_f32_16x16x32_bf16 v[70:73], v[176:179], v[234:237], v[70:73]
	s_barrier
	s_add_i32 s54, s55, s28
	v_lshl_add_u64 v[238:239], s[88:89], 0, v[136:137]
	s_mov_b32 m0, s54
	ds_read_b128 v[180:183], v166 offset:16384
	ds_read_b128 v[184:187], v166 offset:17408
	ds_read_b128 v[188:191], v166 offset:18432
	ds_read_b128 v[192:195], v166 offset:19456
	ds_read_b128 v[208:211], v166 offset:20480
	ds_read_b128 v[226:229], v166 offset:21504
	ds_read_b128 v[230:233], v166 offset:22528
	ds_read_b128 v[234:237], v166 offset:23552
	global_load_lds_dwordx4 v[238:239], off
	s_add_i32 m0, s54, 0x2000
	s_add_u32 s54, s88, 0x40000
	v_lshl_add_u64 v[240:241], s[88:89], 0, v[2:3]
	s_addc_u32 s55, s89, 0
	s_add_i32 s46, s46, s28
	global_load_lds_dwordx4 v[240:241], off
	v_lshl_add_u64 v[242:243], s[54:55], 0, v[136:137]
	s_mov_b32 m0, s46
	v_lshl_add_u64 v[244:245], s[90:91], 0, v[134:135]
	global_load_lds_dwordx4 v[242:243], off
	v_lshl_add_u64 v[242:243], s[54:55], 0, v[2:3]
	s_add_i32 m0, s46, 0x2000
	s_nop 0
	global_load_lds_dwordx4 v[242:243], off
	v_lshl_add_u64 v[242:243], s[90:91], 0, v[138:139]
	s_mov_b32 m0, s30
	s_nop 0
	global_load_lds_dwordx4 v[242:243], off
	s_mov_b32 m0, s31
	s_nop 0
	global_load_lds_dwordx4 v[244:245], off
	s_waitcnt vmcnt(8)
	s_waitcnt lgkmcnt(0)
	s_barrier
	s_waitcnt lgkmcnt(0)
	v_mfma_f32_16x16x32_bf16 v[66:69], v[144:147], v[180:183], v[66:69]
	v_mfma_f32_16x16x32_bf16 v[62:65], v[152:155], v[180:183], v[62:65]
	v_mfma_f32_16x16x32_bf16 v[50:53], v[144:147], v[188:191], v[50:53]
	v_mfma_f32_16x16x32_bf16 v[46:49], v[152:155], v[188:191], v[46:49]
	v_mfma_f32_16x16x32_bf16 v[34:37], v[144:147], v[208:211], v[34:37]
	v_mfma_f32_16x16x32_bf16 v[30:33], v[152:155], v[208:211], v[30:33]
	v_mfma_f32_16x16x32_bf16 v[18:21], v[144:147], v[230:233], v[18:21]
	v_mfma_f32_16x16x32_bf16 v[14:17], v[152:155], v[230:233], v[14:17]
	v_mfma_f32_16x16x32_bf16 v[66:69], v[148:151], v[184:187], v[66:69]
	v_mfma_f32_16x16x32_bf16 v[62:65], v[156:159], v[184:187], v[62:65]
	v_mfma_f32_16x16x32_bf16 v[50:53], v[148:151], v[192:195], v[50:53]
	v_mfma_f32_16x16x32_bf16 v[46:49], v[156:159], v[192:195], v[46:49]
	v_mfma_f32_16x16x32_bf16 v[34:37], v[148:151], v[226:229], v[34:37]
	v_mfma_f32_16x16x32_bf16 v[30:33], v[156:159], v[226:229], v[30:33]
	v_mfma_f32_16x16x32_bf16 v[18:21], v[148:151], v[234:237], v[18:21]
	v_mfma_f32_16x16x32_bf16 v[14:17], v[156:159], v[234:237], v[14:17]
	v_mfma_f32_16x16x32_bf16 v[58:61], v[160:163], v[180:183], v[58:61]
	v_mfma_f32_16x16x32_bf16 v[54:57], v[172:175], v[180:183], v[54:57]
	v_mfma_f32_16x16x32_bf16 v[42:45], v[160:163], v[188:191], v[42:45]
	v_mfma_f32_16x16x32_bf16 v[38:41], v[172:175], v[188:191], v[38:41]
	v_mfma_f32_16x16x32_bf16 v[26:29], v[160:163], v[208:211], v[26:29]
	v_mfma_f32_16x16x32_bf16 v[22:25], v[172:175], v[208:211], v[22:25]
	v_mfma_f32_16x16x32_bf16 v[10:13], v[160:163], v[230:233], v[10:13]
	v_mfma_f32_16x16x32_bf16 v[6:9], v[172:175], v[230:233], v[6:9]
	v_mfma_f32_16x16x32_bf16 v[58:61], v[168:171], v[184:187], v[58:61]
	v_mfma_f32_16x16x32_bf16 v[54:57], v[176:179], v[184:187], v[54:57]
	v_mfma_f32_16x16x32_bf16 v[42:45], v[168:171], v[192:195], v[42:45]
	v_mfma_f32_16x16x32_bf16 v[38:41], v[176:179], v[192:195], v[38:41]
	v_mfma_f32_16x16x32_bf16 v[26:29], v[168:171], v[226:229], v[26:29]
	v_mfma_f32_16x16x32_bf16 v[22:25], v[176:179], v[226:229], v[22:25]
	v_mfma_f32_16x16x32_bf16 v[10:13], v[168:171], v[234:237], v[10:13]
	v_mfma_f32_16x16x32_bf16 v[6:9], v[176:179], v[234:237], v[6:9]
	s_barrier
; #define PG8_STAGE(bufoff, gbase, voff) do { _Pragma("unroll") for (int _i = 0; _i < 2; ++_i) \
;         __builtin_amdgcn_global_load_lds((const unsigned*)((const char*)(gbase) + (voff)[_i]), (PG8_LAS unsigned*)(lds + (bufoff) + ldsw + _i * 8192), 16, 0, 0); } while (0)
; #define PG8_LDA(dst, b, h) do { _Pragma("unroll") for (int m = 0; m < 4; ++m) _Pragma("unroll") for (int k = 0; k < 2; ++k) dst[m][k] = *(const PG8_LAS bf16x8*)(lds + PG8_SA(b, h) + aoff + m * 2048 + k * 1024); } while (0)
; #define PG8_LDB(dst, b, h) do { _Pragma("unroll") for (int n = 0; n < 2; ++n) _Pragma("unroll") for (int k = 0; k < 2; ++k) dst[n][k] = *(const PG8_LAS bf16x8*)(lds + PG8_SB(b, h) + boff + n * 2048 + k * 1024); } while (0)
; #define PG8_MMA(ai, bj, At, Bt) do { __builtin_amdgcn_s_setprio(1); _Pragma("unroll") for (int m = 0; m < 4; ++m) _Pragma("unroll") for (int n = 0; n < 2; ++n) _Pragma("unroll") for (int k = 0; k < 2; ++k) \
;         acc[ai][bj][m][n] = __builtin_amdgcn_mfma_f32_16x16x32_bf16(Bt[n][k], At[m][k], acc[ai][bj][m][n], 0, 0, 0); __builtin_amdgcn_s_setprio(0); } while (0)
; #define PG8_WAIT_V(n) asm volatile("s_waitcnt vmcnt(" #n ")" ::: "memory")
; #define PG8_WAIT_L(n) asm volatile("s_waitcnt lgkmcnt(" #n ")" ::: "memory")
; #define PG8_BAR __builtin_amdgcn_s_barrier()
; #define PG8_SCHED __builtin_amdgcn_sched_barrier(0)
; template <class Epi, class Sched, bool ALIGN_EPI = false, bool SP2 = false>
; __device__ __forceinline__ void gemm_phase(PG8_LAS unsigned char* lds, const Gemm g, const Sched& S, const Epi& E, const int tid) {
;     ...
;             PG8_WAIT_V(8); PG8_WAIT_L(0); PG8_BAR; PG8_MMA(1, 0, At, B0); PG8_MMA(1, 1, At, B1); PG8_BAR; PG8_SCHED;
;             PG8_LDB(B0, 1, 0); PG8_LDB(B1, 1, 1); PG8_SCHED; PG8_LDA(At, 1, 0); PG8_STAGE(PG8_SA(0, 1), a2 + hstep, voffA);
;             PG8_WAIT_V(8); PG8_WAIT_L(0); PG8_BAR; PG8_MMA(0, 0, At, B0); PG8_MMA(0, 1, At, B1); PG8_BAR; PG8_SCHED;
;             PG8_LDA(At, 1, 1); PG8_STAGE(PG8_SB(1, 0), b3, voffB); PG8_STAGE(PG8_SB(1, 1), b3 + hstep, voffB); PG8_STAGE(PG8_SA(1, 0), a3, voffA);
	s_add_i32 s46, 0, 0x18000
	v_add_u32_e32 v0, s46, v164
	s_add_i32 s81, 0, 0x1c000
	ds_read_b128 v[144:147], v0
	ds_read_b128 v[148:151], v0 offset:1024
	ds_read_b128 v[152:155], v0 offset:2048
	ds_read_b128 v[156:159], v0 offset:3072
	v_add_u32_e32 v0, s81, v164
	ds_read_b128 v[160:163], v0
	ds_read_b128 v[168:171], v0 offset:1024
	ds_read_b128 v[172:175], v0 offset:2048
	ds_read_b128 v[176:179], v0 offset:3072
	s_add_u32 s54, s90, 0x40000
	s_addc_u32 s55, s91, 0
	s_mov_b32 m0, s34
	v_lshl_add_u64 v[246:247], s[54:55], 0, v[138:139]
	ds_read_b128 v[180:183], v166 offset:32768
	ds_read_b128 v[184:187], v166 offset:33792
	ds_read_b128 v[188:191], v166 offset:34816
	ds_read_b128 v[192:195], v166 offset:35840
	ds_read_b128 v[208:211], v166 offset:36864
	ds_read_b128 v[226:229], v166 offset:37888
	ds_read_b128 v[230:233], v166 offset:38912
	ds_read_b128 v[234:237], v166 offset:39936
	global_load_lds_dwordx4 v[246:247], off
	v_lshl_add_u64 v[246:247], s[54:55], 0, v[134:135]
	s_mov_b32 m0, s36
	s_nop 0
	global_load_lds_dwordx4 v[246:247], off
	s_waitcnt vmcnt(8)
	s_waitcnt lgkmcnt(0)
	s_barrier
	s_waitcnt lgkmcnt(0)
	v_mfma_f32_16x16x32_bf16 v[130:133], v[144:147], v[180:183], v[130:133]
	v_mfma_f32_16x16x32_bf16 v[126:129], v[152:155], v[180:183], v[126:129]
	v_mfma_f32_16x16x32_bf16 v[114:117], v[144:147], v[188:191], v[114:117]
	v_mfma_f32_16x16x32_bf16 v[110:113], v[152:155], v[188:191], v[110:113]
	v_mfma_f32_16x16x32_bf16 v[98:101], v[144:147], v[208:211], v[98:101]
	v_mfma_f32_16x16x32_bf16 v[94:97], v[152:155], v[208:211], v[94:97]
	v_mfma_f32_16x16x32_bf16 v[82:85], v[144:147], v[230:233], v[82:85]
	v_mfma_f32_16x16x32_bf16 v[78:81], v[152:155], v[230:233], v[78:81]
	v_mfma_f32_16x16x32_bf16 v[130:133], v[148:151], v[184:187], v[130:133]
	v_mfma_f32_16x16x32_bf16 v[126:129], v[156:159], v[184:187], v[126:129]
	v_mfma_f32_16x16x32_bf16 v[114:117], v[148:151], v[192:195], v[114:117]
	v_mfma_f32_16x16x32_bf16 v[110:113], v[156:159], v[192:195], v[110:113]
	v_mfma_f32_16x16x32_bf16 v[98:101], v[148:151], v[226:229], v[98:101]
	v_mfma_f32_16x16x32_bf16 v[94:97], v[156:159], v[226:229], v[94:97]
	v_mfma_f32_16x16x32_bf16 v[82:85], v[148:151], v[234:237], v[82:85]
	v_mfma_f32_16x16x32_bf16 v[78:81], v[156:159], v[234:237], v[78:81]
	v_mfma_f32_16x16x32_bf16 v[122:125], v[160:163], v[180:183], v[122:125]
	v_mfma_f32_16x16x32_bf16 v[118:121], v[172:175], v[180:183], v[118:121]
	v_mfma_f32_16x16x32_bf16 v[106:109], v[160:163], v[188:191], v[106:109]
	v_mfma_f32_16x16x32_bf16 v[102:105], v[172:175], v[188:191], v[102:105]
	v_mfma_f32_16x16x32_bf16 v[90:93], v[160:163], v[208:211], v[90:93]
	v_mfma_f32_16x16x32_bf16 v[86:89], v[172:175], v[208:211], v[86:89]
	v_mfma_f32_16x16x32_bf16 v[74:77], v[160:163], v[230:233], v[74:77]
	v_mfma_f32_16x16x32_bf16 v[70:73], v[172:175], v[230:233], v[70:73]
	v_mfma_f32_16x16x32_bf16 v[122:125], v[168:171], v[184:187], v[122:125]
	v_mfma_f32_16x16x32_bf16 v[118:121], v[176:179], v[184:187], v[118:121]
	v_mfma_f32_16x16x32_bf16 v[106:109], v[168:171], v[192:195], v[106:109]
	v_mfma_f32_16x16x32_bf16 v[102:105], v[176:179], v[192:195], v[102:105]
	v_mfma_f32_16x16x32_bf16 v[90:93], v[168:171], v[226:229], v[90:93]
	v_mfma_f32_16x16x32_bf16 v[86:89], v[176:179], v[226:229], v[86:89]
	v_mfma_f32_16x16x32_bf16 v[74:77], v[168:171], v[234:237], v[74:77]
	v_mfma_f32_16x16x32_bf16 v[70:73], v[176:179], v[234:237], v[70:73]
	s_barrier
	s_add_i32 s46, s46, s28
	v_lshl_add_u64 v[238:239], v[238:239], 0, s[50:51]
	s_mov_b32 m0, s46
	ds_read_b128 v[180:183], v166 offset:49152
	ds_read_b128 v[184:187], v166 offset:50176
	ds_read_b128 v[188:191], v166 offset:51200
	ds_read_b128 v[192:195], v166 offset:52224
	ds_read_b128 v[208:211], v166 offset:53248
	ds_read_b128 v[226:229], v166 offset:54272
	ds_read_b128 v[230:233], v166 offset:55296
	ds_read_b128 v[234:237], v166 offset:56320
	global_load_lds_dwordx4 v[238:239], off
	s_add_i32 m0, s46, 0x2000
	s_add_u32 s54, s88, 0x40080
	v_lshl_add_u64 v[238:239], v[240:241], 0, s[50:51]
	s_addc_u32 s55, s89, 0
	s_add_i32 s46, s81, s28
	global_load_lds_dwordx4 v[238:239], off
	v_lshl_add_u64 v[238:239], s[54:55], 0, v[136:137]
	s_mov_b32 m0, s46
	s_nop 0
	global_load_lds_dwordx4 v[238:239], off
	v_lshl_add_u64 v[238:239], s[54:55], 0, v[2:3]
	s_add_i32 m0, s46, 0x2000
	s_nop 0
	global_load_lds_dwordx4 v[238:239], off
	v_lshl_add_u64 v[238:239], v[242:243], 0, s[50:51]
	s_mov_b32 m0, s37
	s_nop 0
	global_load_lds_dwordx4 v[238:239], off
	v_lshl_add_u64 v[238:239], v[244:245], 0, s[50:51]
	s_mov_b32 m0, s38
	s_nop 0
	global_load_lds_dwordx4 v[238:239], off
	s_waitcnt vmcnt(8)
	s_waitcnt lgkmcnt(0)
	s_barrier
; #define PG8_WAIT_V(n) asm volatile("s_waitcnt vmcnt(" #n ")" ::: "memory")
;     __device__ __forceinline__ void operator()(const f32x4 (&acc)[2][2][4][2], const Unit& u, int wr, int wc, int fr, int fq) const {
;     ...
; #pragma unroll
;             for (int ai = 0; ai < 2; ++ai)
; #pragma unroll
;                 for (int m = 0; m < 4; ++m) {
;                     bf16_t* p = O + (size_t)(row0 + ai * HALF + m * 16) * 3072 + colh;
; #pragma unroll
;                     for (int bj = 0; bj < 2; ++bj) {
;                         const f32x4 v0 = acc[ai][bj][m][0], v1 = acc[ai][bj][m][1];
; template <class Epi, class Sched, bool ALIGN_EPI = false, bool SP2 = false>
; __device__ __forceinline__ void gemm_phase(PG8_LAS unsigned char* lds, const Gemm g, const Sched& S, const Epi& E, const int tid) {
;     ...
;             PG8_WAIT_V(8); PG8_WAIT_L(0); PG8_BAR; PG8_MMA(1, 0, At, B0); PG8_MMA(1, 1, At, B1); PG8_BAR; PG8_SCHED;
;             } else {
;             PG8_LDB(B0, 0, 0); PG8_SCHED; PG8_LDA(At, 0, 0); PG8_STAGE(PG8_SA(1, 1), a1 + hstep, voffA);
;             PG8_WAIT_L(8); PG8_BAR; PG8_WAIT_L(0); PG8_MMA(0, 0, At, B0); PG8_BAR; PG8_SCHED;
;             PG8_LDB(B1, 0, 1); PG8_STAGE(PG8_SB(0, 0), b2, voffB);
;             PG8_BAR; PG8_WAIT_L(0); PG8_MMA(0, 1, At, B1); PG8_BAR;
;             PG8_LDA(At, 0, 1); PG8_STAGE(PG8_SA(0, 0), a2, voffA);
;             PG8_BAR; PG8_WAIT_L(0); PG8_MMA(1, 0, At, B0); PG8_BAR; PG8_SCHED;
;             PG8_STAGE(PG8_SB(0, 1), b2 + hstep, voffB);
;             PG8_WAIT_V(6); PG8_BAR; PG8_MMA(1, 1, At, B1); PG8_BAR;
;             PG8_LDB(B0, 1, 0); PG8_SCHED; PG8_LDA(At, 1, 0); PG8_STAGE(PG8_SA(0, 1), a2 + hstep, voffA);
;             PG8_WAIT_L(8); PG8_BAR; PG8_WAIT_L(0); PG8_MMA(0, 0, At, B0); PG8_BAR; PG8_SCHED;
;             PG8_LDB(B1, 1, 1); PG8_STAGE(PG8_SB(1, 0), b3, voffB);
;             PG8_BAR; PG8_WAIT_L(0); PG8_MMA(0, 1, At, B1); PG8_BAR;
;             PG8_LDA(At, 1, 1); PG8_STAGE(PG8_SA(1, 0), a3, voffA);
;             PG8_BAR; PG8_WAIT_L(0); PG8_MMA(1, 0, At, B0); PG8_BAR; PG8_SCHED;
;             PG8_STAGE(PG8_SB(1, 1), b3 + hstep, voffB);
;             PG8_WAIT_V(6); PG8_BAR; PG8_MMA(1, 1, At, B1); PG8_BAR;
;             }
;         }
;         if constexpr (ALIGN_EPI) { if (wr == 0) PG8_BAR; }
;         if constexpr (!Epi::AFTER_DRAIN) { E(acc, cur, wr, wc, fr, fq); S.done(cur); }
	s_waitcnt lgkmcnt(0)
	v_mfma_f32_16x16x32_bf16 v[66:69], v[144:147], v[180:183], v[66:69]
	v_mfma_f32_16x16x32_bf16 v[62:65], v[152:155], v[180:183], v[62:65]
	v_mfma_f32_16x16x32_bf16 v[50:53], v[144:147], v[188:191], v[50:53]
	v_mfma_f32_16x16x32_bf16 v[46:49], v[152:155], v[188:191], v[46:49]
	v_mfma_f32_16x16x32_bf16 v[34:37], v[144:147], v[208:211], v[34:37]
	v_mfma_f32_16x16x32_bf16 v[30:33], v[152:155], v[208:211], v[30:33]
	v_mfma_f32_16x16x32_bf16 v[18:21], v[144:147], v[230:233], v[18:21]
	v_mfma_f32_16x16x32_bf16 v[14:17], v[152:155], v[230:233], v[14:17]
	v_mfma_f32_16x16x32_bf16 v[66:69], v[148:151], v[184:187], v[66:69]
	v_mfma_f32_16x16x32_bf16 v[62:65], v[156:159], v[184:187], v[62:65]
	v_mfma_f32_16x16x32_bf16 v[50:53], v[148:151], v[192:195], v[50:53]
	v_mfma_f32_16x16x32_bf16 v[46:49], v[156:159], v[192:195], v[46:49]
	v_mfma_f32_16x16x32_bf16 v[34:37], v[148:151], v[226:229], v[34:37]
	v_mfma_f32_16x16x32_bf16 v[30:33], v[156:159], v[226:229], v[30:33]
	v_mfma_f32_16x16x32_bf16 v[18:21], v[148:151], v[234:237], v[18:21]
	v_mfma_f32_16x16x32_bf16 v[14:17], v[156:159], v[234:237], v[14:17]
	v_mfma_f32_16x16x32_bf16 v[58:61], v[160:163], v[180:183], v[58:61]
	v_mfma_f32_16x16x32_bf16 v[54:57], v[172:175], v[180:183], v[54:57]
	v_mfma_f32_16x16x32_bf16 v[42:45], v[160:163], v[188:191], v[42:45]
	v_mfma_f32_16x16x32_bf16 v[38:41], v[172:175], v[188:191], v[38:41]
	v_mfma_f32_16x16x32_bf16 v[26:29], v[160:163], v[208:211], v[26:29]
	v_mfma_f32_16x16x32_bf16 v[22:25], v[172:175], v[208:211], v[22:25]
	v_mfma_f32_16x16x32_bf16 v[10:13], v[160:163], v[230:233], v[10:13]
	v_mfma_f32_16x16x32_bf16 v[6:9], v[172:175], v[230:233], v[6:9]
	v_mfma_f32_16x16x32_bf16 v[58:61], v[168:171], v[184:187], v[58:61]
	v_mfma_f32_16x16x32_bf16 v[54:57], v[176:179], v[184:187], v[54:57]
	v_mfma_f32_16x16x32_bf16 v[42:45], v[168:171], v[192:195], v[42:45]
	v_mfma_f32_16x16x32_bf16 v[38:41], v[176:179], v[192:195], v[38:41]
	v_mfma_f32_16x16x32_bf16 v[26:29], v[168:171], v[226:229], v[26:29]
	v_mfma_f32_16x16x32_bf16 v[22:25], v[176:179], v[226:229], v[22:25]
	v_mfma_f32_16x16x32_bf16 v[10:13], v[168:171], v[234:237], v[10:13]
	v_mfma_f32_16x16x32_bf16 v[6:9], v[176:179], v[234:237], v[6:9]
	s_barrier
	s_add_i32 s43, s43, 2
	s_add_u32 s40, s40, 0x100
	s_addc_u32 s42, s42, 0
	s_add_u32 s6, s6, 0x100
	s_addc_u32 s7, s7, 0
	s_cmp_gt_u32 s43, 13
	s_cbranch_scc0 .LBB0_254
	s_and_b64 vcc, exec, s[78:79]
	s_cbranch_vccz .LBB0_257
	s_barrier
.LBB0_257:
	s_setprio 0
	v_lshl_add_u32 v177, s15, 8, v5
	v_lshl_or_b32 v0, s14, 8, v165
	s_mov_b64 s[6:7], -1
	s_cmp_lt_i32 s14, 4
	v_or_b32_e32 v176, 16, v177
	v_or_b32_e32 v175, 32, v177
	v_or_b32_e32 v174, 48, v177
	v_add_u32_e32 v173, 0x80, v177
	v_add_u32_e32 v172, 0x90, v177
	v_add_u32_e32 v169, 0xa0, v177
	v_add_u32_e32 v168, 0xb0, v177
	s_cbranch_scc1 .LBB0_259
	v_mov_b64_e32 v[148:149], s[8:9]
	v_mad_i64_i32 v[144:145], s[6:7], v177, s44, v[148:149]
	v_lshlrev_b64 v[150:151], 1, v[0:1]
	v_lshl_add_u64 v[152:153], v[144:145], 0, v[150:151]
	v_cvt_pk_bf16_f32 v144, v130, v131
	v_cvt_pk_bf16_f32 v145, v132, v133
	v_cvt_pk_bf16_f32 v146, v126, v127
	v_cvt_pk_bf16_f32 v147, v128, v129
	global_store_dwordx4 v[152:153], v[144:147], off nt
	s_nop 1
	v_cvt_pk_bf16_f32 v144, v122, v123
	v_cvt_pk_bf16_f32 v145, v124, v125
	v_cvt_pk_bf16_f32 v146, v118, v119
	v_cvt_pk_bf16_f32 v147, v120, v121
	global_store_dwordx4 v[152:153], v[144:147], off offset:64 nt
	s_nop 1
	v_mad_i64_i32 v[144:145], s[6:7], v176, s44, v[148:149]
	v_lshl_add_u64 v[152:153], v[144:145], 0, v[150:151]
	v_cvt_pk_bf16_f32 v144, v114, v115
	v_cvt_pk_bf16_f32 v145, v116, v117
	v_cvt_pk_bf16_f32 v146, v110, v111
	v_cvt_pk_bf16_f32 v147, v112, v113
	global_store_dwordx4 v[152:153], v[144:147], off nt
	s_nop 1
	v_cvt_pk_bf16_f32 v144, v106, v107
	v_cvt_pk_bf16_f32 v145, v108, v109
	v_cvt_pk_bf16_f32 v146, v102, v103
	v_cvt_pk_bf16_f32 v147, v104, v105
	global_store_dwordx4 v[152:153], v[144:147], off offset:64 nt
	s_nop 1
	v_mad_i64_i32 v[144:145], s[6:7], v175, s44, v[148:149]
	v_lshl_add_u64 v[152:153], v[144:145], 0, v[150:151]
	v_cvt_pk_bf16_f32 v144, v98, v99
	v_cvt_pk_bf16_f32 v145, v100, v101
	v_cvt_pk_bf16_f32 v146, v94, v95
	v_cvt_pk_bf16_f32 v147, v96, v97
	global_store_dwordx4 v[152:153], v[144:147], off nt
	s_nop 1
	v_cvt_pk_bf16_f32 v144, v90, v91
	v_cvt_pk_bf16_f32 v145, v92, v93
	v_cvt_pk_bf16_f32 v146, v86, v87
	v_cvt_pk_bf16_f32 v147, v88, v89
	global_store_dwordx4 v[152:153], v[144:147], off offset:64 nt
	s_nop 1
	v_mad_i64_i32 v[144:145], s[6:7], v174, s44, v[148:149]
	v_lshl_add_u64 v[152:153], v[144:145], 0, v[150:151]
	v_cvt_pk_bf16_f32 v144, v82, v83
	v_cvt_pk_bf16_f32 v145, v84, v85
	v_cvt_pk_bf16_f32 v146, v78, v79
	v_cvt_pk_bf16_f32 v147, v80, v81
	global_store_dwordx4 v[152:153], v[144:147], off nt
	s_nop 1
	v_cvt_pk_bf16_f32 v144, v74, v75
	v_cvt_pk_bf16_f32 v145, v76, v77
	v_cvt_pk_bf16_f32 v146, v70, v71
	v_cvt_pk_bf16_f32 v147, v72, v73
	global_store_dwordx4 v[152:153], v[144:147], off offset:64 nt
	s_nop 1
	v_mad_i64_i32 v[144:145], s[6:7], v173, s44, v[148:149]
	v_lshl_add_u64 v[152:153], v[144:145], 0, v[150:151]
	v_cvt_pk_bf16_f32 v144, v66, v67
	v_cvt_pk_bf16_f32 v145, v68, v69
	v_cvt_pk_bf16_f32 v146, v62, v63
	v_cvt_pk_bf16_f32 v147, v64, v65
	global_store_dwordx4 v[152:153], v[144:147], off nt
	s_nop 1
	v_cvt_pk_bf16_f32 v144, v58, v59
	v_cvt_pk_bf16_f32 v145, v60, v61
	v_cvt_pk_bf16_f32 v146, v54, v55
	v_cvt_pk_bf16_f32 v147, v56, v57
	global_store_dwordx4 v[152:153], v[144:147], off offset:64 nt
	s_nop 1
	v_mad_i64_i32 v[144:145], s[6:7], v172, s44, v[148:149]
	v_lshl_add_u64 v[152:153], v[144:145], 0, v[150:151]
	v_cvt_pk_bf16_f32 v144, v50, v51
	v_cvt_pk_bf16_f32 v145, v52, v53
	v_cvt_pk_bf16_f32 v146, v46, v47
	v_cvt_pk_bf16_f32 v147, v48, v49
	global_store_dwordx4 v[152:153], v[144:147], off nt
	s_nop 1
	v_cvt_pk_bf16_f32 v144, v42, v43
	v_cvt_pk_bf16_f32 v145, v44, v45
	v_cvt_pk_bf16_f32 v146, v38, v39
	v_cvt_pk_bf16_f32 v147, v40, v41
	global_store_dwordx4 v[152:153], v[144:147], off offset:64 nt
	s_nop 1
	v_mad_i64_i32 v[144:145], s[6:7], v169, s44, v[148:149]
	v_lshl_add_u64 v[152:153], v[144:145], 0, v[150:151]
	v_cvt_pk_bf16_f32 v144, v34, v35
	v_cvt_pk_bf16_f32 v145, v36, v37
	v_cvt_pk_bf16_f32 v146, v30, v31
	v_cvt_pk_bf16_f32 v147, v32, v33
	global_store_dwordx4 v[152:153], v[144:147], off nt
	s_nop 1
	v_cvt_pk_bf16_f32 v144, v26, v27
	v_cvt_pk_bf16_f32 v145, v28, v29
	v_cvt_pk_bf16_f32 v146, v22, v23
	v_cvt_pk_bf16_f32 v147, v24, v25
	global_store_dwordx4 v[152:153], v[144:147], off offset:64 nt
	s_nop 1
	v_mad_i64_i32 v[144:145], s[6:7], v168, s44, v[148:149]
	v_lshl_add_u64 v[160:161], v[144:145], 0, v[150:151]
	v_cvt_pk_bf16_f32 v144, v18, v19
	v_cvt_pk_bf16_f32 v145, v20, v21
	v_cvt_pk_bf16_f32 v146, v14, v15
	v_cvt_pk_bf16_f32 v147, v16, v17
	s_mov_b64 s[6:7], 0
	global_store_dwordx4 v[160:161], v[144:147], off nt

; template <class Epi, class Sched, bool ALIGN_EPI = false, bool SP2 = false>
; __device__ __forceinline__ void gemm_phase(PG8_LAS unsigned char* lds, const Gemm g, const Sched& S, const Epi& E, const int tid) {
;     ...
;         const bool has_next = S.next(ui + 1, nxt);
;         const char* nA = has_next ? (const char*)g.A + (size_t)nxt.pm * tstep : cA; const char* nB = has_next ? (const char*)g.Bt + (size_t)nxt.pn * tstep : cB;
;         for (int t = 0; t < nt; t += 2) {
;             if constexpr (Epi::MIDK) { if (t == E.midk) E.mid(acc, cur, wr, fr); }
;     ...
; #pragma unroll
;         for (int a = 0; a < 2; ++a)
; #pragma unroll
;             for (int b = 0; b < 2; ++b)
; #pragma unroll
;                 for (int m = 0; m < 4; ++m)
; #pragma unroll
;                     for (int n = 0; n < 2; ++n) acc[a][b][m][n] = (f32x4){0.f, 0.f, 0.f, 0.f};
;         cur = nxt; cA = nA; cB = nB; ++ui;
.LBB0_622:
	s_lshl_b32 s42, s25, 8
	s_or_b32 s43, s42, 16
	s_or_b32 s17, s42, 32
	s_or_b32 s95, s42, 48
	s_or_b32 s33, s42, 0x80
	s_or_b32 s14, s42, 0x90
	s_or_b32 s15, s42, 0xa0
	s_or_b32 s98, s42, 0xb0
	s_add_u32 s99, s86, 0x100
	s_addc_u32 s54, s87, 0
	s_add_u32 s4, s84, s97
	s_addc_u32 s5, s85, 0
	s_add_u32 s4, s4, 0x80
	v_mov_b32_e32 v2, v1
	v_mov_b32_e32 v3, v1
	s_addc_u32 s5, s5, 0
	v_mov_b32_e32 v0, v1
	v_mov_b64_e32 v[8:9], v[2:3]
	v_mov_b64_e32 v[12:13], v[2:3]
	v_mov_b64_e32 v[24:25], v[2:3]
	v_mov_b64_e32 v[28:29], v[2:3]
	v_mov_b64_e32 v[40:41], v[2:3]
	v_mov_b64_e32 v[44:45], v[2:3]
	v_mov_b64_e32 v[56:57], v[2:3]
	v_mov_b64_e32 v[60:61], v[2:3]
	v_mov_b64_e32 v[16:17], v[2:3]
	v_mov_b64_e32 v[20:21], v[2:3]
	v_mov_b64_e32 v[32:33], v[2:3]
	v_mov_b64_e32 v[36:37], v[2:3]
	v_mov_b64_e32 v[48:49], v[2:3]
	v_mov_b64_e32 v[52:53], v[2:3]
	v_mov_b64_e32 v[64:65], v[2:3]
	v_mov_b64_e32 v[68:69], v[2:3]
	v_mov_b64_e32 v[72:73], v[2:3]
	v_mov_b64_e32 v[76:77], v[2:3]
	s_waitcnt vmcnt(0)
	v_mov_b64_e32 v[88:89], v[2:3]
	v_mov_b64_e32 v[92:93], v[2:3]
	v_mov_b64_e32 v[104:105], v[2:3]
	v_mov_b64_e32 v[108:109], v[2:3]
	v_mov_b64_e32 v[120:121], v[2:3]
	v_mov_b64_e32 v[124:125], v[2:3]
	v_mov_b64_e32 v[80:81], v[2:3]
	v_mov_b64_e32 v[84:85], v[2:3]
	v_mov_b64_e32 v[96:97], v[2:3]
	v_mov_b64_e32 v[100:101], v[2:3]
	v_mov_b64_e32 v[112:113], v[2:3]
	v_mov_b64_e32 v[116:117], v[2:3]
	v_mov_b64_e32 v[128:129], v[2:3]
	v_mov_b64_e32 v[132:133], v[2:3]
	v_lshl_add_u64 v[134:135], s[4:5], 0, v[166:167]
	v_lshl_add_u64 v[136:137], s[4:5], 0, v[168:169]
	s_mov_b32 s55, 0
	s_mov_b64 s[86:87], 0
	v_mov_b64_e32 v[6:7], v[0:1]
	v_mov_b64_e32 v[10:11], v[0:1]
	v_mov_b64_e32 v[22:23], v[0:1]
	v_mov_b64_e32 v[26:27], v[0:1]
	v_mov_b64_e32 v[38:39], v[0:1]
	v_mov_b64_e32 v[42:43], v[0:1]
	v_mov_b64_e32 v[54:55], v[0:1]
	v_mov_b64_e32 v[58:59], v[0:1]
	v_mov_b64_e32 v[14:15], v[0:1]
	v_mov_b64_e32 v[18:19], v[0:1]
	v_mov_b64_e32 v[30:31], v[0:1]
	v_mov_b64_e32 v[34:35], v[0:1]
	v_mov_b64_e32 v[46:47], v[0:1]
	v_mov_b64_e32 v[50:51], v[0:1]
	v_mov_b64_e32 v[62:63], v[0:1]
	v_mov_b64_e32 v[66:67], v[0:1]
	v_mov_b64_e32 v[70:71], v[0:1]
	v_mov_b64_e32 v[74:75], v[0:1]
	v_mov_b64_e32 v[86:87], v[0:1]
	v_mov_b64_e32 v[90:91], v[0:1]
	v_mov_b64_e32 v[102:103], v[0:1]
	v_mov_b64_e32 v[106:107], v[0:1]
	v_mov_b64_e32 v[118:119], v[0:1]
	v_mov_b64_e32 v[122:123], v[0:1]
	v_mov_b64_e32 v[78:79], v[0:1]
	v_mov_b64_e32 v[82:83], v[0:1]
	v_mov_b64_e32 v[94:95], v[0:1]
	v_mov_b64_e32 v[98:99], v[0:1]
	v_mov_b64_e32 v[110:111], v[0:1]
	v_mov_b64_e32 v[114:115], v[0:1]
	v_mov_b64_e32 v[126:127], v[0:1]
	v_mov_b64_e32 v[130:131], v[0:1]
	s_cmp_eq_u64 s[76:77], 0
	s_cbranch_scc1 .Lprio_res
	s_setprio 1
.Lprio_res:
	s_cmp_lg_u32 s88, s55
	s_cbranch_scc1 .LBB0_624

; #define PG8_STAGE(bufoff, gbase, voff) do { _Pragma("unroll") for (int _i = 0; _i < 2; ++_i) \
;         __builtin_amdgcn_global_load_lds((const unsigned*)((const char*)(gbase) + (voff)[_i]), (PG8_LAS unsigned*)(lds + (bufoff) + ldsw + _i * 8192), 16, 0, 0); } while (0)
; #define PG8_LDA(dst, b, h) do { _Pragma("unroll") for (int m = 0; m < 4; ++m) _Pragma("unroll") for (int k = 0; k < 2; ++k) dst[m][k] = *(const PG8_LAS bf16x8*)(lds + PG8_SA(b, h) + aoff + m * 2048 + k * 1024); } while (0)
; #define PG8_LDB(dst, b, h) do { _Pragma("unroll") for (int n = 0; n < 2; ++n) _Pragma("unroll") for (int k = 0; k < 2; ++k) dst[n][k] = *(const PG8_LAS bf16x8*)(lds + PG8_SB(b, h) + boff + n * 2048 + k * 1024); } while (0)
; #define PG8_WAIT_V(n) asm volatile("s_waitcnt vmcnt(" #n ")" ::: "memory")
; #define PG8_WAIT_L(n) asm volatile("s_waitcnt lgkmcnt(" #n ")" ::: "memory")
; #define PG8_BAR __builtin_amdgcn_s_barrier()
; template <class Epi, class Sched, bool ALIGN_EPI = false, bool SP2 = false>
; __device__ __forceinline__ void gemm_phase(PG8_LAS unsigned char* lds, const Gemm g, const Sched& S, const Epi& E, const int tid) {
;     ...
;         const bool has_next = S.next(ui + 1, nxt);
;         const char* nA = has_next ? (const char*)g.A + (size_t)nxt.pm * tstep : cA; const char* nB = has_next ? (const char*)g.Bt + (size_t)nxt.pn * tstep : cB;
;         for (int t = 0; t < nt; t += 2) {
;             if constexpr (Epi::MIDK) { if (t == E.midk) E.mid(acc, cur, wr, fr); }
;             const bool last = (t == nt - 2);
;             const char* a1 = cA + (size_t)(t + 1) * kstep;
;             const char* a2 = last ? nA : cA + (size_t)(t + 2) * kstep; const char* b2 = last ? nB : cB + (size_t)(t + 2) * kstep;
;             const char* a3 = a2 + kstep; const char* b3 = b2 + kstep;
;             if (last && has_next) S.a_ready(nxt);
;             if constexpr (SP2) {
;             PG8_LDB(B0, 0, 0); PG8_LDB(B1, 0, 1); PG8_SCHED; PG8_LDA(At, 0, 0); PG8_STAGE(PG8_SA(1, 1), a1 + hstep, voffA);
;             PG8_WAIT_V(8); PG8_WAIT_L(0); PG8_BAR; PG8_MMA(0, 0, At, B0); PG8_MMA(0, 1, At, B1); PG8_BAR; PG8_SCHED;
;             PG8_LDA(At, 0, 1); PG8_STAGE(PG8_SB(0, 0), b2, voffB); PG8_STAGE(PG8_SB(0, 1), b2 + hstep, voffB); PG8_STAGE(PG8_SA(0, 0), a2, voffA);
;             PG8_WAIT_V(8); PG8_WAIT_L(0); PG8_BAR; PG8_MMA(1, 0, At, B0); PG8_MMA(1, 1, At, B1); PG8_BAR; PG8_SCHED;
.LBB0_624:
	s_add_i32 vcc_lo, s55, 2
	s_add_u32 s4, s84, s86
	s_addc_u32 s5, s85, s87
	s_add_u32 s4, s4, 0x100
	s_addc_u32 s5, s5, 0
	s_add_u32 s74, s99, s86
	s_addc_u32 s75, s54, s87
	s_add_i32 vcc_hi, 0, 0x10000
	s_cmp_eq_u32 s91, s55
	s_cselect_b32 s5, s81, s5
	s_cselect_b32 s4, s80, s4
	v_add_u32_e32 v0, vcc_hi, v177
	s_cselect_b32 s75, s83, s75
	s_cselect_b32 s74, s82, s74
	s_add_i32 s55, 0, 0x14000
	ds_read_b128 v[138:141], v0
	ds_read_b128 v[142:145], v0 offset:1024
	ds_read_b128 v[146:149], v0 offset:2048
	ds_read_b128 v[150:153], v0 offset:3072
	v_add_u32_e32 v0, s55, v177
	ds_read_b128 v[154:157], v0
	ds_read_b128 v[170:173], v0 offset:1024
	ds_read_b128 v[180:183], v0 offset:2048
	ds_read_b128 v[184:187], v0 offset:3072
	v_lshl_add_u64 v[2:3], v[136:137], 0, s[86:87]
	s_add_i32 m0, s20, 0xc000
	ds_read_b128 v[188:191], v179
	ds_read_b128 v[192:195], v179 offset:1024
	ds_read_b128 v[208:211], v179 offset:2048
	ds_read_b128 v[226:229], v179 offset:3072
	ds_read_b128 v[230:233], v179 offset:4096
	ds_read_b128 v[234:237], v179 offset:5120
	ds_read_b128 v[238:241], v179 offset:6144
	ds_read_b128 v[242:245], v179 offset:7168
	global_load_lds_dwordx4 v[2:3], off
	v_lshl_add_u64 v[2:3], v[134:135], 0, s[86:87]
	s_add_i32 m0, s20, 0xe000
	s_nop 0
	global_load_lds_dwordx4 v[2:3], off
	s_waitcnt vmcnt(8)
	s_waitcnt lgkmcnt(0)
	s_barrier
	s_waitcnt lgkmcnt(0)
	v_mfma_f32_16x16x32_bf16 v[130:133], v[138:141], v[188:191], v[130:133]
	v_mfma_f32_16x16x32_bf16 v[126:129], v[146:149], v[188:191], v[126:129]
	v_mfma_f32_16x16x32_bf16 v[114:117], v[138:141], v[208:211], v[114:117]
	v_mfma_f32_16x16x32_bf16 v[110:113], v[146:149], v[208:211], v[110:113]
	v_mfma_f32_16x16x32_bf16 v[98:101], v[138:141], v[230:233], v[98:101]
	v_mfma_f32_16x16x32_bf16 v[94:97], v[146:149], v[230:233], v[94:97]
	v_mfma_f32_16x16x32_bf16 v[82:85], v[138:141], v[238:241], v[82:85]
	v_mfma_f32_16x16x32_bf16 v[78:81], v[146:149], v[238:241], v[78:81]
	v_mfma_f32_16x16x32_bf16 v[130:133], v[142:145], v[192:195], v[130:133]
	v_mfma_f32_16x16x32_bf16 v[126:129], v[150:153], v[192:195], v[126:129]
	v_mfma_f32_16x16x32_bf16 v[114:117], v[142:145], v[226:229], v[114:117]
	v_mfma_f32_16x16x32_bf16 v[110:113], v[150:153], v[226:229], v[110:113]
	v_mfma_f32_16x16x32_bf16 v[98:101], v[142:145], v[234:237], v[98:101]
	v_mfma_f32_16x16x32_bf16 v[94:97], v[150:153], v[234:237], v[94:97]
	v_mfma_f32_16x16x32_bf16 v[82:85], v[142:145], v[242:245], v[82:85]
	v_mfma_f32_16x16x32_bf16 v[78:81], v[150:153], v[242:245], v[78:81]
	v_mfma_f32_16x16x32_bf16 v[122:125], v[154:157], v[188:191], v[122:125]
	v_mfma_f32_16x16x32_bf16 v[118:121], v[180:183], v[188:191], v[118:121]
	v_mfma_f32_16x16x32_bf16 v[106:109], v[154:157], v[208:211], v[106:109]
	v_mfma_f32_16x16x32_bf16 v[102:105], v[180:183], v[208:211], v[102:105]
	v_mfma_f32_16x16x32_bf16 v[90:93], v[154:157], v[230:233], v[90:93]
	v_mfma_f32_16x16x32_bf16 v[86:89], v[180:183], v[230:233], v[86:89]
	v_mfma_f32_16x16x32_bf16 v[74:77], v[154:157], v[238:241], v[74:77]
	v_mfma_f32_16x16x32_bf16 v[70:73], v[180:183], v[238:241], v[70:73]
	v_mfma_f32_16x16x32_bf16 v[122:125], v[170:173], v[192:195], v[122:125]
	v_mfma_f32_16x16x32_bf16 v[118:121], v[184:187], v[192:195], v[118:121]
	v_mfma_f32_16x16x32_bf16 v[106:109], v[170:173], v[226:229], v[106:109]
	v_mfma_f32_16x16x32_bf16 v[102:105], v[184:187], v[226:229], v[102:105]
	v_mfma_f32_16x16x32_bf16 v[90:93], v[170:173], v[234:237], v[90:93]
	v_mfma_f32_16x16x32_bf16 v[86:89], v[184:187], v[234:237], v[86:89]
	v_mfma_f32_16x16x32_bf16 v[74:77], v[170:173], v[242:245], v[74:77]
	v_mfma_f32_16x16x32_bf16 v[70:73], v[184:187], v[242:245], v[70:73]
	s_barrier
	s_add_i32 vcc_hi, vcc_hi, s19
	v_lshl_add_u64 v[2:3], s[74:75], 0, v[162:163]
	s_mov_b32 m0, vcc_hi
	ds_read_b128 v[188:191], v179 offset:16384
	ds_read_b128 v[192:195], v179 offset:17408
	ds_read_b128 v[208:211], v179 offset:18432
	ds_read_b128 v[226:229], v179 offset:19456
	ds_read_b128 v[230:233], v179 offset:20480
	ds_read_b128 v[234:237], v179 offset:21504
	ds_read_b128 v[238:241], v179 offset:22528
	ds_read_b128 v[242:245], v179 offset:23552
	global_load_lds_dwordx4 v[2:3], off
	s_add_i32 m0, vcc_hi, 0x2000
	v_lshl_add_u64 v[174:175], s[74:75], 0, v[158:159]
	s_add_u32 s74, s74, s97
	s_addc_u32 s75, s75, 0
	s_add_i32 s55, s55, s19
	global_load_lds_dwordx4 v[174:175], off
	v_lshl_add_u64 v[246:247], s[74:75], 0, v[162:163]
	s_mov_b32 m0, s55
	v_lshl_add_u64 v[248:249], s[74:75], 0, v[158:159]
	global_load_lds_dwordx4 v[246:247], off
	s_add_i32 m0, s55, 0x2000
	v_lshl_add_u64 v[250:251], s[4:5], 0, v[164:165]
	global_load_lds_dwordx4 v[248:249], off
	s_mov_b32 m0, s20
	v_lshl_add_u64 v[252:253], s[4:5], 0, v[160:161]
	global_load_lds_dwordx4 v[250:251], off
	s_mov_b32 m0, s21
	s_nop 0
	global_load_lds_dwordx4 v[252:253], off
	s_waitcnt vmcnt(8)
	s_waitcnt lgkmcnt(0)
	s_barrier
; #define PG8_STAGE(bufoff, gbase, voff) do { _Pragma("unroll") for (int _i = 0; _i < 2; ++_i) \
;         __builtin_amdgcn_global_load_lds((const unsigned*)((const char*)(gbase) + (voff)[_i]), (PG8_LAS unsigned*)(lds + (bufoff) + ldsw + _i * 8192), 16, 0, 0); } while (0)
; #define PG8_LDA(dst, b, h) do { _Pragma("unroll") for (int m = 0; m < 4; ++m) _Pragma("unroll") for (int k = 0; k < 2; ++k) dst[m][k] = *(const PG8_LAS bf16x8*)(lds + PG8_SA(b, h) + aoff + m * 2048 + k * 1024); } while (0)
; #define PG8_LDB(dst, b, h) do { _Pragma("unroll") for (int n = 0; n < 2; ++n) _Pragma("unroll") for (int k = 0; k < 2; ++k) dst[n][k] = *(const PG8_LAS bf16x8*)(lds + PG8_SB(b, h) + boff + n * 2048 + k * 1024); } while (0)
; #define PG8_MMA(ai, bj, At, Bt) do { __builtin_amdgcn_s_setprio(1); _Pragma("unroll") for (int m = 0; m < 4; ++m) _Pragma("unroll") for (int n = 0; n < 2; ++n) _Pragma("unroll") for (int k = 0; k < 2; ++k) \
;         acc[ai][bj][m][n] = __builtin_amdgcn_mfma_f32_16x16x32_bf16(Bt[n][k], At[m][k], acc[ai][bj][m][n], 0, 0, 0); __builtin_amdgcn_s_setprio(0); } while (0)
; #define PG8_WAIT_V(n) asm volatile("s_waitcnt vmcnt(" #n ")" ::: "memory")
; #define PG8_WAIT_L(n) asm volatile("s_waitcnt lgkmcnt(" #n ")" ::: "memory")
; #define PG8_BAR __builtin_amdgcn_s_barrier()
; #define PG8_SCHED __builtin_amdgcn_sched_barrier(0)
; template <class Epi, class Sched, bool ALIGN_EPI = false, bool SP2 = false>
; __device__ __forceinline__ void gemm_phase(PG8_LAS unsigned char* lds, const Gemm g, const Sched& S, const Epi& E, const int tid) {
;     ...
;             PG8_WAIT_V(8); PG8_WAIT_L(0); PG8_BAR; PG8_MMA(1, 0, At, B0); PG8_MMA(1, 1, At, B1); PG8_BAR; PG8_SCHED;
;             PG8_LDB(B0, 1, 0); PG8_LDB(B1, 1, 1); PG8_SCHED; PG8_LDA(At, 1, 0); PG8_STAGE(PG8_SA(0, 1), a2 + hstep, voffA);
;             PG8_WAIT_V(8); PG8_WAIT_L(0); PG8_BAR; PG8_MMA(0, 0, At, B0); PG8_MMA(0, 1, At, B1); PG8_BAR; PG8_SCHED;
	s_waitcnt lgkmcnt(0)
	v_mfma_f32_16x16x32_bf16 v[66:69], v[138:141], v[188:191], v[66:69]
	v_mfma_f32_16x16x32_bf16 v[62:65], v[146:149], v[188:191], v[62:65]
	v_mfma_f32_16x16x32_bf16 v[50:53], v[138:141], v[208:211], v[50:53]
	v_mfma_f32_16x16x32_bf16 v[46:49], v[146:149], v[208:211], v[46:49]
	v_mfma_f32_16x16x32_bf16 v[34:37], v[138:141], v[230:233], v[34:37]
	v_mfma_f32_16x16x32_bf16 v[30:33], v[146:149], v[230:233], v[30:33]
	v_mfma_f32_16x16x32_bf16 v[18:21], v[138:141], v[238:241], v[18:21]
	v_mfma_f32_16x16x32_bf16 v[14:17], v[146:149], v[238:241], v[14:17]
	v_mfma_f32_16x16x32_bf16 v[66:69], v[142:145], v[192:195], v[66:69]
	v_mfma_f32_16x16x32_bf16 v[62:65], v[150:153], v[192:195], v[62:65]
	v_mfma_f32_16x16x32_bf16 v[50:53], v[142:145], v[226:229], v[50:53]
	v_mfma_f32_16x16x32_bf16 v[46:49], v[150:153], v[226:229], v[46:49]
	v_mfma_f32_16x16x32_bf16 v[34:37], v[142:145], v[234:237], v[34:37]
	v_mfma_f32_16x16x32_bf16 v[30:33], v[150:153], v[234:237], v[30:33]
	v_mfma_f32_16x16x32_bf16 v[18:21], v[142:145], v[242:245], v[18:21]
	v_mfma_f32_16x16x32_bf16 v[14:17], v[150:153], v[242:245], v[14:17]
	v_mfma_f32_16x16x32_bf16 v[58:61], v[154:157], v[188:191], v[58:61]
	v_mfma_f32_16x16x32_bf16 v[54:57], v[180:183], v[188:191], v[54:57]
	v_mfma_f32_16x16x32_bf16 v[42:45], v[154:157], v[208:211], v[42:45]
	v_mfma_f32_16x16x32_bf16 v[38:41], v[180:183], v[208:211], v[38:41]
	v_mfma_f32_16x16x32_bf16 v[26:29], v[154:157], v[230:233], v[26:29]
	v_mfma_f32_16x16x32_bf16 v[22:25], v[180:183], v[230:233], v[22:25]
	v_mfma_f32_16x16x32_bf16 v[10:13], v[154:157], v[238:241], v[10:13]
	v_mfma_f32_16x16x32_bf16 v[6:9], v[180:183], v[238:241], v[6:9]
	v_mfma_f32_16x16x32_bf16 v[58:61], v[170:173], v[192:195], v[58:61]
	v_mfma_f32_16x16x32_bf16 v[54:57], v[184:187], v[192:195], v[54:57]
	v_mfma_f32_16x16x32_bf16 v[42:45], v[170:173], v[226:229], v[42:45]
	v_mfma_f32_16x16x32_bf16 v[38:41], v[184:187], v[226:229], v[38:41]
	v_mfma_f32_16x16x32_bf16 v[26:29], v[170:173], v[234:237], v[26:29]
	v_mfma_f32_16x16x32_bf16 v[22:25], v[184:187], v[234:237], v[22:25]
	v_mfma_f32_16x16x32_bf16 v[10:13], v[170:173], v[242:245], v[10:13]
	v_mfma_f32_16x16x32_bf16 v[6:9], v[184:187], v[242:245], v[6:9]
	s_barrier
	s_add_i32 s55, 0, 0x18000
	v_add_u32_e32 v0, s55, v177
	s_add_i32 s74, 0, 0x1c000
	ds_read_b128 v[138:141], v0
	ds_read_b128 v[142:145], v0 offset:1024
	ds_read_b128 v[146:149], v0 offset:2048
	ds_read_b128 v[150:153], v0 offset:3072
	v_add_u32_e32 v0, s74, v177
	ds_read_b128 v[154:157], v0
	ds_read_b128 v[170:173], v0 offset:1024
	ds_read_b128 v[180:183], v0 offset:2048
	ds_read_b128 v[184:187], v0 offset:3072
	s_add_u32 s4, s4, s97
	s_addc_u32 s5, s5, 0
	s_mov_b32 m0, s28
	v_lshl_add_u64 v[222:223], s[4:5], 0, v[164:165]
	ds_read_b128 v[188:191], v179 offset:32768
	ds_read_b128 v[192:195], v179 offset:33792
	ds_read_b128 v[208:211], v179 offset:34816
	ds_read_b128 v[226:229], v179 offset:35840
	ds_read_b128 v[230:233], v179 offset:36864
	ds_read_b128 v[234:237], v179 offset:37888
	ds_read_b128 v[238:241], v179 offset:38912
	ds_read_b128 v[242:245], v179 offset:39936
	global_load_lds_dwordx4 v[222:223], off
	v_lshl_add_u64 v[222:223], s[4:5], 0, v[160:161]
	s_mov_b32 m0, s13
	s_nop 0
	global_load_lds_dwordx4 v[222:223], off
	s_waitcnt vmcnt(8)
	s_waitcnt lgkmcnt(0)
	s_barrier
	s_waitcnt lgkmcnt(0)
	v_mfma_f32_16x16x32_bf16 v[130:133], v[138:141], v[188:191], v[130:133]
	v_mfma_f32_16x16x32_bf16 v[126:129], v[146:149], v[188:191], v[126:129]
	v_mfma_f32_16x16x32_bf16 v[114:117], v[138:141], v[208:211], v[114:117]
	v_mfma_f32_16x16x32_bf16 v[110:113], v[146:149], v[208:211], v[110:113]
	v_mfma_f32_16x16x32_bf16 v[98:101], v[138:141], v[230:233], v[98:101]
	v_mfma_f32_16x16x32_bf16 v[94:97], v[146:149], v[230:233], v[94:97]
	v_mfma_f32_16x16x32_bf16 v[82:85], v[138:141], v[238:241], v[82:85]
	v_mfma_f32_16x16x32_bf16 v[78:81], v[146:149], v[238:241], v[78:81]
	v_mfma_f32_16x16x32_bf16 v[130:133], v[142:145], v[192:195], v[130:133]
	v_mfma_f32_16x16x32_bf16 v[126:129], v[150:153], v[192:195], v[126:129]
	v_mfma_f32_16x16x32_bf16 v[114:117], v[142:145], v[226:229], v[114:117]
	v_mfma_f32_16x16x32_bf16 v[110:113], v[150:153], v[226:229], v[110:113]
	v_mfma_f32_16x16x32_bf16 v[98:101], v[142:145], v[234:237], v[98:101]
	v_mfma_f32_16x16x32_bf16 v[94:97], v[150:153], v[234:237], v[94:97]
	v_mfma_f32_16x16x32_bf16 v[82:85], v[142:145], v[242:245], v[82:85]
	v_mfma_f32_16x16x32_bf16 v[78:81], v[150:153], v[242:245], v[78:81]
	v_mfma_f32_16x16x32_bf16 v[122:125], v[154:157], v[188:191], v[122:125]
	v_mfma_f32_16x16x32_bf16 v[118:121], v[180:183], v[188:191], v[118:121]
	v_mfma_f32_16x16x32_bf16 v[106:109], v[154:157], v[208:211], v[106:109]
	v_mfma_f32_16x16x32_bf16 v[102:105], v[180:183], v[208:211], v[102:105]
	v_mfma_f32_16x16x32_bf16 v[90:93], v[154:157], v[230:233], v[90:93]
	v_mfma_f32_16x16x32_bf16 v[86:89], v[180:183], v[230:233], v[86:89]
	v_mfma_f32_16x16x32_bf16 v[74:77], v[154:157], v[238:241], v[74:77]
	v_mfma_f32_16x16x32_bf16 v[70:73], v[180:183], v[238:241], v[70:73]
	v_mfma_f32_16x16x32_bf16 v[122:125], v[170:173], v[192:195], v[122:125]
	v_mfma_f32_16x16x32_bf16 v[118:121], v[184:187], v[192:195], v[118:121]
	v_mfma_f32_16x16x32_bf16 v[106:109], v[170:173], v[226:229], v[106:109]
	v_mfma_f32_16x16x32_bf16 v[102:105], v[184:187], v[226:229], v[102:105]
	v_mfma_f32_16x16x32_bf16 v[90:93], v[170:173], v[234:237], v[90:93]
	v_mfma_f32_16x16x32_bf16 v[86:89], v[184:187], v[234:237], v[86:89]
	v_mfma_f32_16x16x32_bf16 v[74:77], v[170:173], v[242:245], v[74:77]
	v_mfma_f32_16x16x32_bf16 v[70:73], v[184:187], v[242:245], v[70:73]
	s_barrier
; #define PG8_GAS __attribute__((address_space(1)))
; #define PG8_STAGE(bufoff, gbase, voff) do { _Pragma("unroll") for (int _i = 0; _i < 2; ++_i) \
;         __builtin_amdgcn_global_load_lds((const unsigned*)((const char*)(gbase) + (voff)[_i]), (PG8_LAS unsigned*)(lds + (bufoff) + ldsw + _i * 8192), 16, 0, 0); } while (0)
; #define PG8_LDA(dst, b, h) do { _Pragma("unroll") for (int m = 0; m < 4; ++m) _Pragma("unroll") for (int k = 0; k < 2; ++k) dst[m][k] = *(const PG8_LAS bf16x8*)(lds + PG8_SA(b, h) + aoff + m * 2048 + k * 1024); } while (0)
;     __device__ __forceinline__ void operator()(const f32x4 (&acc)[2][2][4][2], const Unit& u, int wr, int wc, int fr, int fq) const {
;         const int b = (u.pm * BM) >> 13;
;         const float* gp = mod + b * 9216 + step * 3072 + 2048; const float coef = step == 1 ? 1.0f : 0.5f;
;         const float* basef = step == 0 ? xin : (const float*)nullptr; const bf16_t* baseb = xs; bf16_t* out = xs;
;         const int col0 = u.pn * BM + wc * 32 + 8 * fq;
;         f32x4 gv[2][2];
; #pragma unroll
;         for (int bj = 0; bj < 2; ++bj)
; #pragma unroll
;             for (int n = 0; n < 2; ++n) gv[bj][n] = (*(const PG8_GAS f32x4*)(gp + col0 + bj * HALF + 4 * n) + 1.0f) * coef;
; #pragma unroll
;         for (int ai = 0; ai < 2; ++ai)
; #pragma unroll
;             for (int m = 0; m < 4; ++m) {
;                 const size_t off = (size_t)(u.pm * BM + ai * HALF + wr * 64 + m * 16 + fr) * 1024 + col0;
; #pragma unroll
;                 for (int bj = 0; bj < 2; ++bj) {
;                     f32x4 b0, b1;
;                     if (basef) { b0 = __builtin_nontemporal_load((const PG8_GAS f32x4*)(basef + off + bj * HALF)); b1 = __builtin_nontemporal_load((const PG8_GAS f32x4*)(basef + off + bj * HALF + 4)); }
; template <class Epi, class Sched, bool ALIGN_EPI = false, bool SP2 = false>
; __device__ __forceinline__ void gemm_phase(PG8_LAS unsigned char* lds, const Gemm g, const Sched& S, const Epi& E, const int tid) {
;     ...
;             PG8_WAIT_V(8); PG8_WAIT_L(0); PG8_BAR; PG8_MMA(0, 0, At, B0); PG8_MMA(0, 1, At, B1); PG8_BAR; PG8_SCHED;
;             PG8_LDA(At, 1, 1); PG8_STAGE(PG8_SB(1, 0), b3, voffB); PG8_STAGE(PG8_SB(1, 1), b3 + hstep, voffB); PG8_STAGE(PG8_SA(1, 0), a3, voffA);
;             PG8_WAIT_V(8); PG8_WAIT_L(0); PG8_BAR; PG8_MMA(1, 0, At, B0); PG8_MMA(1, 1, At, B1); PG8_BAR; PG8_SCHED;
	s_add_i32 s4, s55, s19
	v_lshl_add_u64 v[2:3], v[2:3], 0, s[50:51]
	s_mov_b32 m0, s4
	ds_read_b128 v[188:191], v179 offset:49152
	ds_read_b128 v[192:195], v179 offset:50176
	ds_read_b128 v[208:211], v179 offset:51200
	ds_read_b128 v[226:229], v179 offset:52224
	ds_read_b128 v[230:233], v179 offset:53248
	ds_read_b128 v[234:237], v179 offset:54272
	ds_read_b128 v[238:241], v179 offset:55296
	ds_read_b128 v[242:245], v179 offset:56320
	global_load_lds_dwordx4 v[2:3], off
	v_lshl_add_u64 v[2:3], v[174:175], 0, s[50:51]
	s_add_i32 m0, s4, 0x2000
	s_add_i32 s4, s74, s19
	global_load_lds_dwordx4 v[2:3], off
	v_lshl_add_u64 v[2:3], v[246:247], 0, s[50:51]
	s_mov_b32 m0, s4
	s_nop 0
	global_load_lds_dwordx4 v[2:3], off
	v_lshl_add_u64 v[2:3], v[248:249], 0, s[50:51]
	s_add_i32 m0, s4, 0x2000
	s_nop 0
	global_load_lds_dwordx4 v[2:3], off
	v_lshl_add_u64 v[2:3], v[250:251], 0, s[50:51]
	s_mov_b32 m0, s36
	s_nop 0
	global_load_lds_dwordx4 v[2:3], off
	v_lshl_add_u64 v[2:3], v[252:253], 0, s[50:51]
	s_mov_b32 m0, s46
	s_nop 0
	global_load_lds_dwordx4 v[2:3], off
	s_waitcnt vmcnt(8)
	s_waitcnt lgkmcnt(0)
	s_barrier
	s_waitcnt lgkmcnt(0)
	v_mfma_f32_16x16x32_bf16 v[66:69], v[138:141], v[188:191], v[66:69]
	v_mfma_f32_16x16x32_bf16 v[62:65], v[146:149], v[188:191], v[62:65]
	v_mfma_f32_16x16x32_bf16 v[50:53], v[138:141], v[208:211], v[50:53]
	v_mfma_f32_16x16x32_bf16 v[46:49], v[146:149], v[208:211], v[46:49]
	v_mfma_f32_16x16x32_bf16 v[34:37], v[138:141], v[230:233], v[34:37]
	v_mfma_f32_16x16x32_bf16 v[30:33], v[146:149], v[230:233], v[30:33]
	v_mfma_f32_16x16x32_bf16 v[18:21], v[138:141], v[238:241], v[18:21]
	v_mfma_f32_16x16x32_bf16 v[14:17], v[146:149], v[238:241], v[14:17]
	v_mfma_f32_16x16x32_bf16 v[66:69], v[142:145], v[192:195], v[66:69]
	v_mfma_f32_16x16x32_bf16 v[62:65], v[150:153], v[192:195], v[62:65]
	v_mfma_f32_16x16x32_bf16 v[50:53], v[142:145], v[226:229], v[50:53]
	v_mfma_f32_16x16x32_bf16 v[46:49], v[150:153], v[226:229], v[46:49]
	v_mfma_f32_16x16x32_bf16 v[34:37], v[142:145], v[234:237], v[34:37]
	v_mfma_f32_16x16x32_bf16 v[30:33], v[150:153], v[234:237], v[30:33]
	v_mfma_f32_16x16x32_bf16 v[18:21], v[142:145], v[242:245], v[18:21]
	v_mfma_f32_16x16x32_bf16 v[14:17], v[150:153], v[242:245], v[14:17]
	v_mfma_f32_16x16x32_bf16 v[58:61], v[154:157], v[188:191], v[58:61]
	v_mfma_f32_16x16x32_bf16 v[54:57], v[180:183], v[188:191], v[54:57]
	v_mfma_f32_16x16x32_bf16 v[42:45], v[154:157], v[208:211], v[42:45]
	v_mfma_f32_16x16x32_bf16 v[38:41], v[180:183], v[208:211], v[38:41]
	v_mfma_f32_16x16x32_bf16 v[26:29], v[154:157], v[230:233], v[26:29]
	v_mfma_f32_16x16x32_bf16 v[22:25], v[180:183], v[230:233], v[22:25]
	v_mfma_f32_16x16x32_bf16 v[10:13], v[154:157], v[238:241], v[10:13]
	v_mfma_f32_16x16x32_bf16 v[6:9], v[180:183], v[238:241], v[6:9]
	v_mfma_f32_16x16x32_bf16 v[58:61], v[170:173], v[192:195], v[58:61]
	v_mfma_f32_16x16x32_bf16 v[54:57], v[184:187], v[192:195], v[54:57]
	v_mfma_f32_16x16x32_bf16 v[42:45], v[170:173], v[226:229], v[42:45]
	v_mfma_f32_16x16x32_bf16 v[38:41], v[184:187], v[226:229], v[38:41]
	v_mfma_f32_16x16x32_bf16 v[26:29], v[170:173], v[234:237], v[26:29]
	v_mfma_f32_16x16x32_bf16 v[22:25], v[184:187], v[234:237], v[22:25]
	v_mfma_f32_16x16x32_bf16 v[10:13], v[170:173], v[242:245], v[10:13]
	v_mfma_f32_16x16x32_bf16 v[6:9], v[184:187], v[242:245], v[6:9]
	s_barrier
	s_add_u32 s86, s86, 0x100
	s_addc_u32 s87, s87, 0
	s_cmp_ge_u32 vcc_lo, s30
	s_cbranch_scc1 .LBB0_626
	s_mov_b32 s55, vcc_lo
	s_cmp_lg_u32 s88, s55
	s_cbranch_scc0 .LBB0_623
	s_branch .LBB0_624
.LBB0_626:
.LBB0_628:
	s_setprio 0
	s_lshr_b32 s4, s25, 5
	s_mulk_i32 s4, 0x2400
	s_ashr_i32 s5, s4, 31
	s_lshl_b64 s[4:5], s[4:5], 2
	s_add_u32 s4, s38, s4
	v_lshl_or_b32 v2, s40, 8, v178
	s_addc_u32 s5, s18, s5
	v_ashrrev_i32_e32 v3, 31, v2
	v_lshl_add_u64 v[134:135], v[2:3], 2, s[4:5]
	s_mov_b64 s[4:5], 0x2000
	v_lshl_add_u64 v[138:139], v[134:135], 0, s[4:5]
	v_add_co_u32_e32 v134, vcc, s47, v134
	v_add_u32_e32 v170, s42, v176
	s_nop 0
	v_addc_co_u32_e32 v135, vcc, 0, v135, vcc
	global_load_dwordx4 v[146:149], v[134:135], off
	s_nop 0
	global_load_dwordx4 v[134:137], v[138:139], off offset:528
	global_load_dwordx4 v[142:145], v[138:139], off offset:16
	s_nop 0
	global_load_dwordx4 v[138:141], v[138:139], off offset:512
	v_ashrrev_i32_e32 v171, 31, v170
	v_lshlrev_b64 v[150:151], 10, v[170:171]
	v_lshl_add_u64 v[150:151], v[150:151], 0, v[2:3]
	v_lshl_add_u64 v[2:3], v[150:151], 1, s[56:57]
	v_lshl_add_u64 v[174:175], v[150:151], 2, s[64:65]
	v_mov_b64_e32 v[182:183], v[2:3]
	s_andn2_b64 vcc, exec, s[66:67]
	s_cbranch_vccnz .Lres_epi_bf16
	s_mov_b32 s4, 0x10000
	s_mov_b32 s5, 0
	s_mov_b32 vcc_lo, 0x50000
	s_mov_b32 vcc_hi, 0
	global_load_dwordx4 v[150:153], v[174:175], off nt
	global_load_dwordx4 v[154:157], v[174:175], off offset:16 nt
	global_load_dwordx4 v[170:173], v[174:175], off offset:512 nt
	global_load_dwordx4 v[184:187], v[174:175], off offset:528 nt
	v_lshl_add_u64 v[174:175], v[174:175], 0, s[4:5]
	global_load_dwordx4 v[188:191], v[174:175], off nt
	global_load_dwordx4 v[192:195], v[174:175], off offset:16 nt
	global_load_dwordx4 v[208:211], v[174:175], off offset:512 nt
	global_load_dwordx4 v[226:229], v[174:175], off offset:528 nt
	v_lshl_add_u64 v[174:175], v[174:175], 0, s[4:5]
	global_load_dwordx4 v[230:233], v[174:175], off nt
	global_load_dwordx4 v[234:237], v[174:175], off offset:16 nt
	global_load_dwordx4 v[238:241], v[174:175], off offset:512 nt
	global_load_dwordx4 v[242:245], v[174:175], off offset:528 nt
	v_lshl_add_u64 v[174:175], v[174:175], 0, s[4:5]
	global_load_dwordx4 v[246:249], v[174:175], off nt
	global_load_dwordx4 v[250:253], v[174:175], off offset:16 nt
	s_cmp_eq_u64 s[78:79], 0
	s_cbranch_scc1 .Lres_nb_f32
	s_barrier
